# MLA items claimed from per-head queues (XCD pair prefers one head) + scan loader waves global loads with counted vmcnt + MLA staging loads global
# speedup vs baseline: 1.0149x; 1.0055x over previous
; __global__ void __launch_bounds__(NT) fwd_megakernel(Params P0) {
;     ...
;       int* sitem = (int*)(smem + 159744);
;       for (;;) {
;         if (tid == 0) *sitem = atomicAdd(ctrl + 16 * l, 1);
;         __syncthreads(); const int item = *sitem; __syncthreads();
;         if (item >= 16 + 512 + 256) break;
;         if (item < 16) gdn_scan_item(P, l, item >> 1, item & 1, smem);
;         else if (item < 528) { const int idx = item - 16; mla_attn_item(P, idx & 3, 127 - (idx >> 2), smem); }
;         else { const int idx = item - 528; swa_item(P, l, idx >> 1, idx & 1, smem); }
.LBB0_592:
	s_or_b64 exec, exec, s[4:5]
	s_waitcnt vmcnt(0)
	v_readfirstlane_b32 s4, v2
	s_nop 1
	v_add_u32_e32 v0, s4, v0
	s_cmp_lt_u32 s4, 16
	s_cbranch_scc1 .Lmq_done
	s_cmpk_gt_u32 s4, 0x20f
	s_cbranch_scc1 .Lmq_done
	s_getreg_b32 s5, hwreg(HW_REG_XCC_ID, 0, 4)
	s_lshr_b32 s5, s5, 1
	s_and_b32 s5, s5, 3
	s_mov_b32 s8, 4
.Lmq_try:
	s_lshl_b32 s9, s5, 2
	s_add_u32 s9, s9, 4
	v_mov_b32_e32 v2, 1
	v_mov_b32_e32 v3, s9
	global_atomic_add v2, v3, v2, s[0:1] sc0
	s_waitcnt vmcnt(0)
	v_readfirstlane_b32 s9, v2
	s_nop 1
	s_cmpk_lt_u32 s9, 0x80
	s_cbranch_scc1 .Lmq_got
	s_add_u32 s5, s5, 1
	s_and_b32 s5, s5, 3
	s_sub_u32 s8, s8, 1
	s_cmp_lg_u32 s8, 0
	s_cbranch_scc1 .Lmq_try
	s_branch .Lmq_done
.Lmq_got:
	s_lshl_b32 s9, s9, 2
	s_add_u32 s9, s9, s5
	s_add_u32 s9, s9, 16
	v_mov_b32_e32 v0, s9
.Lmq_done:
	ds_write_b32 v238, v0

; DI int opaque_tid() { int t = threadIdx.x; asm volatile("" : "+v"(t)); return t; }
; DI void mla_attn_item(const Params& P, int hd, int b, char* smem) {
;   const int tid = opaque_tid(), lane = tid & 63, w = tid >> 6, wq = w & 3, hk = w >> 2, lq = lane & 31, h = lane >> 5;
;   const float* qraw = (const float*)(P.ws + OFF_QRAW);
;   const bf16_t* Kg = (const bf16_t*)(P.ws + OFF_KMLA) + (size_t)hd * S_ * 192;
;   const bf16_t* Vg = (const bf16_t*)(P.ws + OFF_VT) + (size_t)hd * 128 * S_;
;   bf16_t* mixin = (bf16_t*)(P.ws + OFF_H);
;   const int q = 128 * b + 32 * wq + lq;
;   bf16x8 qf[12];
;   {
;     const float* qp = qraw + (size_t)q * 768 + hd * 192 + 8 * h;
;     const float sc = 0.07216878364870322f * LOG2E;
; #pragma unroll
;     for (int s = 0; s < 8; ++s) { const f32x4 a = *(const f32x4*)(qp + 16 * s), c = *(const f32x4*)(qp + 16 * s + 4);
;       qf[s] = pack8(a.x * sc, a.y * sc, a.z * sc, a.w * sc, c.x * sc, c.y * sc, c.z * sc, c.w * sc); }
;     const double pq = (double)P.pos[q];
; #pragma unroll
;     for (int s2 = 0; s2 < 2; ++s2) {
;       const f32x4 a0 = *(const f32x4*)(qp + 128 + 16 * s2), a1 = *(const f32x4*)(qp + 128 + 16 * s2 + 4);
;       const f32x4 b0 = *(const f32x4*)(qp + 160 + 16 * s2), b1 = *(const f32x4*)(qp + 160 + 16 * s2 + 4);
;       float x1[8] = {a0.x, a0.y, a0.z, a0.w, a1.x, a1.y, a1.z, a1.w}, x2[8] = {b0.x, b0.y, b0.z, b0.w, b1.x, b1.y, b1.z, b1.w}, o1[8], o2[8];
; #pragma unroll
;       for (int j = 0; j < 8; ++j) { double fr = pq * kInvFreq2Pi[16 * s2 + 8 * h + j]; fr -= floor(fr); const float ff = (float)fr;
;         const float sn = __builtin_amdgcn_sinf(ff), cs = __builtin_amdgcn_cosf(ff);
;         o1[j] = (x1[j] * cs - x2[j] * sn) * sc; o2[j] = (x2[j] * cs + x1[j] * sn) * sc; }
;       qf[8 + s2] = pack8(o1[0], o1[1], o1[2], o1[3], o1[4], o1[5], o1[6], o1[7]);
;       qf[10 + s2] = pack8(o2[0], o2[1], o2[2], o2[3], o2[4], o2[5], o2[6], o2[7]);
;     }
;   }
;   constexpr int KST = 64 * 400, VST = 128 * 144, STG = KST + VST;
;   f32x16 O[4];
; #pragma unroll
;   for (int i = 0; i < 4; ++i)
; #pragma unroll
;     for (int r = 0; r < 16; ++r) O[i][r] = 0.f;
;   float m_i = -1e30f, l_i = 0.f;
;   const int nt = 2 * b + 2;
;   u32x4 rk0[3], rv0[2], rk1[3], rv1[2];
.LBB0_640:
	s_and_b64 vcc, exec, s[2:3]
	s_cbranch_vccz .LBB0_660
	v_mov_b32_e32 v187, v206
	global_load_dwordx2 v[184:185], v1, s[40:41] offset:1224
	global_load_dwordx2 v[2:3], v1, s[40:41] offset:1040
	s_add_i32 s2, s96, -16
	s_lshr_b32 s8, s2, 2
	v_bfe_u32 v209, v187, 6, 2
	s_sub_i32 s9, 0x7f, s8
	v_lshlrev_b32_e32 v39, 5, v209
	v_and_b32_e32 v38, 31, v187
	v_lshl_or_b32 v213, s9, 7, v39
	s_and_b32 s97, s96, 3
	v_or_b32_e32 v186, v213, v38
	s_movk_i32 s4, 0xc00
	s_mov_b32 s3, s63
	s_mul_i32 s2, s97, 0x300
	v_and_b32_e32 v0, 32, v187
	v_bfe_u32 v40, v187, 5, 1
	v_lshlrev_b32_e32 v41, 6, v40
	s_mul_i32 s62, s97, 0x600000
	v_ashrrev_i32_e32 v221, 8, v187
	v_lshlrev_b32_e32 v216, 2, v40
	v_lshlrev_b32_e32 v222, 6, v221
	s_movk_i32 s61, 0x100
	v_and_b32_e32 v215, 63, v187
	v_lshrrev_b32_e32 v214, 6, v187
	v_mov_b32_e32 v229, 0xf149f2ca
	v_mov_b32_e32 v212, 0
	s_mov_b32 s60, -2
	s_waitcnt vmcnt(0)
	v_mad_u64_u32 v[4:5], s[4:5], v186, s4, v[184:185]
	v_lshl_add_u64 v[4:5], v[4:5], 0, s[2:3]
	v_lshl_add_u64 v[4:5], v[4:5], 0, v[0:1]
	s_mov_b32 s2, 0xa2e8000
	v_add_co_u32_e32 v6, vcc, s2, v4
	s_mov_b64 s[2:3], 0xa2e8000
	v_lshlrev_b32_e32 v0, 2, v186
	v_addc_co_u32_e32 v7, vcc, 0, v5, vcc
	v_lshl_add_u64 v[18:19], v[4:5], 0, s[2:3]
	v_lshl_add_u64 v[2:3], v[2:3], 0, v[0:1]
	flat_load_dwordx4 v[20:23], v[6:7]
	flat_load_dwordx4 v[24:27], v[18:19] offset:16
	flat_load_dwordx4 v[28:31], v[18:19] offset:64
	flat_load_dwordx4 v[32:35], v[18:19] offset:80
	flat_load_dwordx4 v[42:45], v[18:19] offset:128
	flat_load_dwordx4 v[46:49], v[18:19] offset:144
	flat_load_dwordx4 v[50:53], v[18:19] offset:192
	flat_load_dwordx4 v[54:57], v[18:19] offset:208
	flat_load_dwordx4 v[58:61], v[18:19] offset:256
	flat_load_dwordx4 v[62:65], v[18:19] offset:272
	flat_load_dwordx4 v[66:69], v[18:19] offset:320
	flat_load_dwordx4 v[70:73], v[18:19] offset:336
	flat_load_dwordx4 v[74:77], v[18:19] offset:384
	flat_load_dwordx4 v[78:81], v[18:19] offset:400
	flat_load_dwordx4 v[82:85], v[18:19] offset:448
	flat_load_dword v0, v[2:3]
	s_getpc_b64 s[4:5]
	s_add_u32 s4, s4, kInvFreq2Pi@rel32@lo+4
	s_addc_u32 s5, s5, kInvFreq2Pi@rel32@hi+12
	flat_load_dwordx4 v[86:89], v[18:19] offset:464
	global_load_dwordx4 v[90:93], v41, s[4:5] offset:16
	global_load_dwordx4 v[128:131], v41, s[4:5]
	s_getpc_b64 s[2:3]
	s_add_u32 s2, s2, kInvFreq2Pi@rel32@lo+132
	s_addc_u32 s3, s3, kInvFreq2Pi@rel32@hi+140
	global_load_dwordx4 v[132:135], v41, s[4:5] offset:48
	global_load_dwordx4 v[136:139], v41, s[4:5] offset:32
	global_load_dwordx4 v[10:13], v41, s[2:3] offset:16
	global_load_dwordx4 v[14:17], v41, s[2:3]
	flat_load_dwordx4 v[140:143], v[18:19] offset:512
	flat_load_dwordx4 v[144:147], v[18:19] offset:528
	flat_load_dwordx4 v[148:151], v[18:19] offset:656
	flat_load_dwordx4 v[152:155], v[18:19] offset:640
	flat_load_dwordx4 v[2:5], v[18:19] offset:592
	flat_load_dwordx4 v[6:9], v[18:19] offset:720
	v_lshl_add_u64 v[36:37], v[184:185], 0, s[62:63]
	s_lshl_b32 s62, s97, 22
	s_mov_b64 s[4:5], 0xd2e8000
	v_lshl_add_u64 v[188:189], v[36:37], 0, s[4:5]
	s_lshl_b32 s56, s9, 1
	s_or_b32 s57, s56, 1
	s_waitcnt vmcnt(0) lgkmcnt(0)
	v_pk_mul_f32 v[24:25], v[24:25], s[54:55] op_sel_hi:[1,0]
	v_pk_mul_f32 v[26:27], v[26:27], s[54:55] op_sel_hi:[1,0]
	v_pk_mul_f32 v[94:95], v[34:35], s[54:55] op_sel_hi:[1,0]
	v_pk_mul_f32 v[28:29], v[28:29], s[54:55] op_sel_hi:[1,0]
	v_pk_mul_f32 v[30:31], v[30:31], s[54:55] op_sel_hi:[1,0]
	v_cvt_pk_bf16_f32 v98, v24, v25
	v_cvt_pk_bf16_f32 v99, v26, v27
	v_cvt_pk_bf16_f32 v100, v28, v29
	v_cvt_pk_bf16_f32 v101, v30, v31
	v_pk_mul_f32 v[46:47], v[46:47], s[54:55] op_sel_hi:[1,0]
	v_pk_mul_f32 v[32:33], v[32:33], s[54:55] op_sel_hi:[1,0]
	v_cvt_pk_bf16_f32 v106, v46, v47
	v_pk_mul_f32 v[20:21], v[20:21], s[54:55] op_sel_hi:[1,0]
	v_pk_mul_f32 v[22:23], v[22:23], s[54:55] op_sel_hi:[1,0]
	v_cvt_f64_i32_e32 v[34:35], v0
	v_cvt_pk_bf16_f32 v96, v20, v21
	v_cvt_pk_bf16_f32 v97, v22, v23
	v_mul_f64 v[20:21], v[128:129], v[34:35]
	v_mul_f64 v[22:23], v[130:131], v[34:35]
	v_mul_f64 v[24:25], v[90:91], v[34:35]
	v_mul_f64 v[26:27], v[92:93], v[34:35]
	v_mul_f64 v[28:29], v[136:137], v[34:35]
	v_mul_f64 v[30:31], v[138:139], v[34:35]
	v_floor_f64_e32 v[20:21], v[20:21]
	v_floor_f64_e32 v[22:23], v[22:23]
	v_floor_f64_e32 v[24:25], v[24:25]
	v_floor_f64_e32 v[26:27], v[26:27]
	v_floor_f64_e32 v[28:29], v[28:29]
	v_floor_f64_e32 v[30:31], v[30:31]
	v_fma_f64 v[20:21], v[128:129], v[34:35], -v[20:21]
	v_fma_f64 v[22:23], v[130:131], v[34:35], -v[22:23]
	v_fma_f64 v[24:25], v[90:91], v[34:35], -v[24:25]
	v_fma_f64 v[26:27], v[92:93], v[34:35], -v[26:27]
	v_fma_f64 v[28:29], v[136:137], v[34:35], -v[28:29]
	v_fma_f64 v[30:31], v[138:139], v[34:35], -v[30:31]
	v_cvt_f32_f64_e32 v0, v[20:21]
	v_cvt_f32_f64_e32 v23, v[22:23]
	v_cvt_f32_f64_e32 v25, v[24:25]
	v_cvt_f32_f64_e32 v27, v[26:27]
	v_cvt_f32_f64_e32 v46, v[28:29]
	v_cvt_f32_f64_e32 v47, v[30:31]
	v_sin_f32_e32 v20, v0
	v_sin_f32_e32 v21, v23
	v_sin_f32_e32 v24, v25
	v_cos_f32_e32 v26, v25
	v_sin_f32_e32 v25, v27
	v_cos_f32_e32 v22, v0
	v_cos_f32_e32 v23, v23
	v_cos_f32_e32 v27, v27
	v_sin_f32_e32 v30, v46
	v_sin_f32_e32 v31, v47
	v_cos_f32_e32 v46, v46
	v_cos_f32_e32 v47, v47
	v_pk_mul_f32 v[48:49], v[48:49], s[54:55] op_sel_hi:[1,0]
	v_cvt_pk_bf16_f32 v102, v32, v33
	v_pk_mul_f32 v[28:29], v[152:153], v[20:21]
	v_pk_mul_f32 v[20:21], v[140:141], v[20:21]
	v_pk_mul_f32 v[32:33], v[154:155], v[24:25]
	v_pk_mul_f32 v[24:25], v[142:143], v[24:25]
	v_pk_mul_f32 v[42:43], v[42:43], s[54:55] op_sel_hi:[1,0]
	v_pk_mul_f32 v[44:45], v[44:45], s[54:55] op_sel_hi:[1,0]
	v_cvt_pk_bf16_f32 v107, v48, v49
; DI void mla_attn_item(const Params& P, int hd, int b, char* smem) {
;     ...
;     const double pq = (double)P.pos[q];
; #pragma unroll
;     for (int s2 = 0; s2 < 2; ++s2) {
;       const f32x4 a0 = *(const f32x4*)(qp + 128 + 16 * s2), a1 = *(const f32x4*)(qp + 128 + 16 * s2 + 4);
;       const f32x4 b0 = *(const f32x4*)(qp + 160 + 16 * s2), b1 = *(const f32x4*)(qp + 160 + 16 * s2 + 4);
;       float x1[8] = {a0.x, a0.y, a0.z, a0.w, a1.x, a1.y, a1.z, a1.w}, x2[8] = {b0.x, b0.y, b0.z, b0.w, b1.x, b1.y, b1.z, b1.w}, o1[8], o2[8];
; #pragma unroll
;       for (int j = 0; j < 8; ++j) { double fr = pq * kInvFreq2Pi[16 * s2 + 8 * h + j]; fr -= floor(fr); const float ff = (float)fr;
;         const float sn = __builtin_amdgcn_sinf(ff), cs = __builtin_amdgcn_cosf(ff);
;         o1[j] = (x1[j] * cs - x2[j] * sn) * sc; o2[j] = (x2[j] * cs + x1[j] * sn) * sc; }
;       qf[8 + s2] = pack8(o1[0], o1[1], o1[2], o1[3], o1[4], o1[5], o1[6], o1[7]);
;       qf[10 + s2] = pack8(o2[0], o2[1], o2[2], o2[3], o2[4], o2[5], o2[6], o2[7]);
;     }
;   }
;   constexpr int KST = 64 * 400, VST = 128 * 144, STG = KST + VST;
;   f32x16 O[4];
; #pragma unroll
;   for (int i = 0; i < 4; ++i)
; #pragma unroll
;     for (int r = 0; r < 16; ++r) O[i][r] = 0.f;
;   float m_i = -1e30f, l_i = 0.f;
;   const int nt = 2 * b + 2;
;   u32x4 rk0[3], rv0[2], rk1[3], rv1[2];
;   const int vrow = tid >> 3, vcc = tid & 7;
;   const int ntl = nt - 1;
	v_pk_fma_f32 v[28:29], v[140:141], v[22:23], v[28:29] neg_lo:[0,0,1] neg_hi:[0,0,1]
	v_pk_fma_f32 v[20:21], v[152:153], v[22:23], v[20:21]
	v_pk_fma_f32 v[22:23], v[142:143], v[26:27], v[32:33] neg_lo:[0,0,1] neg_hi:[0,0,1]
	v_pk_fma_f32 v[24:25], v[154:155], v[26:27], v[24:25]
	v_pk_mul_f32 v[48:49], v[148:149], v[30:31]
	v_pk_mul_f32 v[52:53], v[52:53], s[54:55] op_sel_hi:[1,0]
	v_cvt_pk_bf16_f32 v104, v42, v43
	v_cvt_pk_bf16_f32 v105, v44, v45
	v_pk_mul_f32 v[32:33], v[28:29], s[54:55] op_sel_hi:[1,0]
	v_pk_mul_f32 v[42:43], v[22:23], s[54:55] op_sel_hi:[1,0]
	v_pk_mul_f32 v[44:45], v[24:25], s[54:55] op_sel_hi:[1,0]
	flat_load_dwordx4 v[22:25], v[18:19] offset:704
	flat_load_dwordx4 v[26:29], v[18:19] offset:576
	v_pk_fma_f32 v[18:19], v[144:145], v[46:47], v[48:49] neg_lo:[0,0,1] neg_hi:[0,0,1]
	v_mul_f64 v[48:49], v[132:133], v[34:35]
	v_cvt_pk_bf16_f32 v109, v52, v53
	v_floor_f64_e32 v[48:49], v[48:49]
	v_mul_f64 v[52:53], v[134:135], v[34:35]
	v_fma_f64 v[48:49], v[132:133], v[34:35], -v[48:49]
	v_floor_f64_e32 v[52:53], v[52:53]
	v_pk_mul_f32 v[50:51], v[50:51], s[54:55] op_sel_hi:[1,0]
	v_cvt_f32_f64_e32 v0, v[48:49]
	v_fma_f64 v[52:53], v[134:135], v[34:35], -v[52:53]
	v_cvt_pk_bf16_f32 v108, v50, v51
	v_sin_f32_e32 v48, v0
	v_cos_f32_e32 v50, v0
	v_cvt_f32_f64_e32 v0, v[52:53]
	v_sin_f32_e32 v49, v0
	v_cos_f32_e32 v51, v0
	v_pk_mul_f32 v[30:31], v[144:145], v[30:31]
	v_pk_mul_f32 v[62:63], v[62:63], s[54:55] op_sel_hi:[1,0]
	v_pk_fma_f32 v[30:31], v[148:149], v[46:47], v[30:31]
	v_cvt_pk_bf16_f32 v114, v62, v63
	v_pk_mul_f32 v[62:63], v[30:31], s[54:55] op_sel_hi:[1,0]
	v_pk_mul_f32 v[30:31], v[150:151], v[48:49]
	v_pk_mul_f32 v[66:67], v[66:67], s[54:55] op_sel_hi:[1,0]
	v_pk_fma_f32 v[30:31], v[146:147], v[50:51], v[30:31] neg_lo:[0,0,1] neg_hi:[0,0,1]
	v_pk_mul_f32 v[20:21], v[20:21], s[54:55] op_sel_hi:[1,0]
	v_pk_mul_f32 v[18:19], v[18:19], s[54:55] op_sel_hi:[1,0]
	v_pk_mul_f32 v[30:31], v[30:31], s[54:55] op_sel_hi:[1,0]
	v_cvt_pk_bf16_f32 v129, v42, v43
	v_mul_f64 v[42:43], v[14:15], v[34:35]
	v_pk_mul_f32 v[68:69], v[68:69], s[54:55] op_sel_hi:[1,0]
	v_cvt_pk_bf16_f32 v116, v66, v67
	v_cvt_pk_bf16_f32 v128, v32, v33
	v_cvt_pk_bf16_f32 v130, v18, v19
	v_cvt_pk_bf16_f32 v131, v30, v31
	v_cvt_pk_bf16_f32 v132, v20, v21
	global_load_dwordx4 v[18:21], v41, s[2:3] offset:48
	global_load_dwordx4 v[30:33], v41, s[2:3] offset:32
	v_floor_f64_e32 v[66:67], v[42:43]
	v_lshl_add_u64 v[42:43], v[184:185], 0, s[62:63]
	s_mov_b64 s[2:3], 0xeae8000
	v_cvt_pk_bf16_f32 v117, v68, v69
	v_lshl_add_u64 v[68:69], v[42:43], 0, s[2:3]
	s_mov_b32 s3, 0x2aaaaaab
	v_mul_hi_i32 v0, v187, s3
	v_lshrrev_b32_e32 v41, 31, v0
	v_ashrrev_i32_e32 v0, 2, v0
	v_add_u32_e32 v41, v0, v41
	v_pk_mul_f32 v[86:87], v[86:87], s[54:55] op_sel_hi:[1,0]
	v_mul_lo_u32 v0, v41, 24
	v_cvt_pk_bf16_f32 v126, v86, v87
	v_sub_u32_e32 v86, v187, v0
	v_add_u32_e32 v0, 0x200, v187
	v_cvt_pk_bf16_f32 v133, v44, v45
	v_mul_hi_i32 v44, v0, s3
	v_lshrrev_b32_e32 v45, 31, v44
	v_ashrrev_i32_e32 v44, 2, v44
	v_add_u32_e32 v87, v44, v45
	v_pk_mul_f32 v[88:89], v[88:89], s[54:55] op_sel_hi:[1,0]
	v_mul_lo_u32 v44, v87, 24
	v_cvt_pk_bf16_f32 v127, v88, v89
	v_pk_mul_f32 v[46:47], v[146:147], v[48:49]
	v_sub_u32_e32 v88, v0, v44
	v_add_u32_e32 v0, 0x400, v187
	v_pk_fma_f32 v[46:47], v[150:151], v[50:51], v[46:47]
	v_mul_hi_i32 v50, v0, s3
	v_lshrrev_b32_e32 v51, 31, v50
	v_ashrrev_i32_e32 v50, 2, v50
	v_add_u32_e32 v89, v50, v51
	s_movk_i32 s2, 0xc0
	v_mul_lo_u32 v50, v89, 24
	v_pk_mul_f32 v[82:83], v[82:83], s[54:55] op_sel_hi:[1,0]
	v_mul_lo_u32 v190, v41, s2
	v_mul_lo_u32 v194, v87, s2
	v_sub_u32_e32 v90, v0, v50
	v_mul_lo_u32 v198, v89, s2
	v_pk_mul_f32 v[70:71], v[70:71], s[54:55] op_sel_hi:[1,0]
	v_pk_mul_f32 v[74:75], v[74:75], s[54:55] op_sel_hi:[1,0]
	v_pk_mul_f32 v[78:79], v[78:79], s[54:55] op_sel_hi:[1,0]
	v_cvt_pk_bf16_f32 v124, v82, v83
	v_ashrrev_i32_e32 v191, 31, v190
	v_lshlrev_b32_e32 v192, 3, v86
	v_ashrrev_i32_e32 v195, 31, v194
	v_lshlrev_b32_e32 v196, 3, v88
	v_ashrrev_i32_e32 v199, 31, v198
	v_lshlrev_b32_e32 v200, 3, v90
	v_ashrrev_i32_e32 v82, 3, v187
	v_lshlrev_b32_e32 v0, 4, v187
	v_pk_mul_f32 v[72:73], v[72:73], s[54:55] op_sel_hi:[1,0]
	v_pk_mul_f32 v[76:77], v[76:77], s[54:55] op_sel_hi:[1,0]
	v_pk_mul_f32 v[80:81], v[80:81], s[54:55] op_sel_hi:[1,0]
	v_cvt_pk_bf16_f32 v118, v70, v71
	v_cvt_pk_bf16_f32 v120, v74, v75
	v_cvt_pk_bf16_f32 v122, v78, v79
	v_lshlrev_b64 v[70:71], 1, v[190:191]
	v_ashrrev_i32_e32 v193, 31, v192
	v_lshlrev_b64 v[74:75], 1, v[194:195]
	v_ashrrev_i32_e32 v197, 31, v196
	v_lshlrev_b64 v[78:79], 1, v[198:199]
	v_ashrrev_i32_e32 v201, 31, v200
	v_and_b32_e32 v0, 0x70, v0
	v_ashrrev_i32_e32 v83, 31, v82
	v_pk_mul_f32 v[54:55], v[54:55], s[54:55] op_sel_hi:[1,0]
	v_pk_mul_f32 v[64:65], v[64:65], s[54:55] op_sel_hi:[1,0]
	v_cvt_pk_bf16_f32 v119, v72, v73
	v_cvt_pk_bf16_f32 v121, v76, v77
	v_cvt_pk_bf16_f32 v123, v80, v81
	v_lshl_add_u64 v[42:43], v[188:189], 0, v[70:71]
	v_lshlrev_b64 v[72:73], 1, v[192:193]
	v_lshl_add_u64 v[44:45], v[188:189], 0, v[74:75]
	v_lshlrev_b64 v[76:77], 1, v[196:197]
	v_lshl_add_u64 v[50:51], v[188:189], 0, v[78:79]
	v_lshlrev_b64 v[80:81], 1, v[200:201]
	v_lshl_add_u64 v[202:203], v[68:69], 0, v[0:1]
	v_lshlrev_b64 v[204:205], 15, v[82:83]
	s_mov_b64 s[2:3], 0x200000
	v_pk_mul_f32 v[56:57], v[56:57], s[54:55] op_sel_hi:[1,0]
	v_pk_mul_f32 v[58:59], v[58:59], s[54:55] op_sel_hi:[1,0]
	v_cvt_pk_bf16_f32 v110, v54, v55
	v_cvt_pk_bf16_f32 v115, v64, v65
	v_pk_mul_f32 v[64:65], v[46:47], s[54:55] op_sel_hi:[1,0]
	v_lshl_add_u64 v[42:43], v[42:43], 0, v[72:73]
	v_lshl_add_u64 v[46:47], v[44:45], 0, v[76:77]
	v_lshl_add_u64 v[50:51], v[50:51], 0, v[80:81]
	v_lshl_add_u64 v[54:55], v[202:203], 0, v[204:205]
	v_lshl_add_u64 v[210:211], v[204:205], 0, s[2:3]
	v_pk_mul_f32 v[60:61], v[60:61], s[54:55] op_sel_hi:[1,0]
	v_cvt_pk_bf16_f32 v111, v56, v57
	v_cvt_pk_bf16_f32 v112, v58, v59
	flat_load_dwordx4 v[42:45], v[42:43]
	s_nop 0
	flat_load_dwordx4 v[46:49], v[46:47]
	s_nop 0
	flat_load_dwordx4 v[50:53], v[50:51]
	s_nop 0
	flat_load_dwordx4 v[54:57], v[54:55]
	v_lshl_add_u64 v[58:59], v[202:203], 0, v[210:211]
	v_cvt_pk_bf16_f32 v113, v60, v61
	flat_load_dwordx4 v[58:61], v[58:59]
	v_pk_mul_f32 v[84:85], v[84:85], s[54:55] op_sel_hi:[1,0]
	v_fma_f64 v[14:15], v[14:15], v[34:35], -v[66:67]
	v_cvt_pk_bf16_f32 v125, v84, v85
	v_mul_f64 v[84:85], v[16:17], v[34:35]
	v_floor_f64_e32 v[84:85], v[84:85]
	v_fma_f64 v[16:17], v[16:17], v[34:35], -v[84:85]
	v_cvt_f32_f64_e32 v15, v[14:15]
	v_cvt_f32_f64_e32 v16, v[16:17]
	v_sin_f32_e32 v14, v15
	v_cos_f32_e32 v66, v15
	v_sin_f32_e32 v15, v16
	v_cos_f32_e32 v67, v16
	v_cvt_pk_bf16_f32 v134, v62, v63
	v_mul_f64 v[62:63], v[12:13], v[34:35]
	s_waitcnt vmcnt(0) lgkmcnt(0)
; #define AT_LOAD(RK, RV, T) { const size_t ko_ = (size_t)(T) * 64 * 192; const int vo_ = (T) * 64; \
;     _Pragma("unroll") for (int i = 0; i < 3; ++i) { const int id = tid + NT * i, row = id / 24, cc = id % 24; RK[i] = *(const u32x4*)(Kg + ko_ + row * 192 + cc * 8); } \
;     _Pragma("unroll") for (int i = 0; i < 2; ++i) RV[i] = *(const u32x4*)(Vg + (size_t)(vrow + 64 * i) * S_ + vo_ + vcc * 8); }
; #define AT_WRITE(RK, RV, ST) { char* dK = smem + (ST) * STG; \
;     _Pragma("unroll") for (int i = 0; i < 3; ++i) { const int id = tid + NT * i, row = id / 24, cc = id % 24; *(u32x4*)(dK + row * 400 + cc * 16) = RK[i]; } \
;     _Pragma("unroll") for (int i = 0; i < 2; ++i) *(u32x4*)(dK + KST + (vrow + 64 * i) * 144 + vcc * 16) = RV[i]; }
; DI void mla_attn_item(const Params& P, int hd, int b, char* smem) {
;     ...
;   f32x16 O[4];
; #pragma unroll
;   for (int i = 0; i < 4; ++i)
; #pragma unroll
;     for (int r = 0; r < 16; ++r) O[i][r] = 0.f;
;     ...
;   AT_LOAD(rk0, rv0, 0);
;   AT_LOAD(rk1, rv1, 1);
;   AT_WRITE(rk0, rv0, 0);
;   AT_LOAD(rk0, rv0, (2 < ntl ? 2 : ntl));
;   __syncthreads();
	v_pk_mul_f32 v[16:17], v[22:23], v[14:15]
	v_pk_mul_f32 v[14:15], v[26:27], v[14:15]
	v_pk_fma_f32 v[16:17], v[26:27], v[66:67], v[16:17] neg_lo:[0,0,1] neg_hi:[0,0,1]
	v_mul_f64 v[26:27], v[10:11], v[34:35]
	v_floor_f64_e32 v[26:27], v[26:27]
	v_floor_f64_e32 v[62:63], v[62:63]
	v_fma_f64 v[10:11], v[10:11], v[34:35], -v[26:27]
	v_fma_f64 v[12:13], v[12:13], v[34:35], -v[62:63]
	v_cvt_f32_f64_e32 v11, v[10:11]
	v_cvt_f32_f64_e32 v12, v[12:13]
	v_sin_f32_e32 v10, v11
	v_cos_f32_e32 v26, v11
	v_sin_f32_e32 v11, v12
	v_cos_f32_e32 v27, v12
	v_pk_fma_f32 v[12:13], v[22:23], v[66:67], v[14:15]
	s_mov_b64 s[2:3], 0xd2ee000
	v_pk_mul_f32 v[14:15], v[24:25], v[10:11]
	v_pk_mul_f32 v[10:11], v[28:29], v[10:11]
	v_pk_fma_f32 v[14:15], v[28:29], v[26:27], v[14:15] neg_lo:[0,0,1] neg_hi:[0,0,1]
	v_pk_fma_f32 v[10:11], v[24:25], v[26:27], v[10:11]
	v_mul_f64 v[26:27], v[32:33], v[34:35]
	v_floor_f64_e32 v[26:27], v[26:27]
	v_fma_f64 v[26:27], v[32:33], v[34:35], -v[26:27]
	v_cvt_f32_f64_e32 v25, v[26:27]
	v_lshl_add_u64 v[26:27], v[36:37], 0, s[2:3]
	v_lshl_add_u64 v[28:29], v[26:27], 0, v[70:71]
	v_lshl_add_u64 v[28:29], v[28:29], 0, v[72:73]
	global_load_dwordx4 v[136:139], v[28:29], off
	v_lshl_add_u64 v[28:29], v[26:27], 0, v[74:75]
	v_lshl_add_u64 v[26:27], v[26:27], 0, v[78:79]
	v_lshl_add_u64 v[28:29], v[28:29], 0, v[76:77]
	v_lshl_add_u64 v[26:27], v[26:27], 0, v[80:81]
	global_load_dwordx4 v[140:143], v[28:29], off
	global_load_dwordx4 v[144:147], v[26:27], off
	v_lshl_add_u64 v[26:27], v[68:69], 0, v[204:205]
	v_lshl_add_u64 v[26:27], v[26:27], 0, v[0:1]
	v_lshl_add_u64 v[28:29], v[68:69], 0, v[210:211]
	s_movk_i32 s3, 0x190
	v_lshl_add_u64 v[28:29], v[28:29], 0, v[0:1]
	global_load_dwordx4 v[148:151], v[26:27], off offset:128
	global_load_dwordx4 v[152:155], v[28:29], off offset:128
	v_mul_lo_u32 v26, v41, s3
	v_lshlrev_b32_e32 v27, 4, v86
	s_movk_i32 s2, 0x90
	v_add_u32_e32 v217, v26, v27
	v_mul_lo_u32 v26, v87, s3
	v_lshlrev_b32_e32 v27, 4, v88
	v_mul_lo_u32 v32, v82, s2
	s_min_u32 s2, s57, 2
	v_add_u32_e32 v218, v26, v27
	v_mul_lo_u32 v26, v89, s3
	v_lshlrev_b32_e32 v27, 4, v90
	s_mul_i32 s62, s2, 0x6000
	v_mul_f64 v[22:23], v[30:31], v[34:35]
	v_add_u32_e32 v219, v26, v27
	v_lshl_add_u64 v[26:27], v[188:189], 0, s[62:63]
	v_floor_f64_e32 v[22:23], v[22:23]
	v_add_u32_e32 v220, v0, v32
	v_lshl_add_u64 v[28:29], v[26:27], 0, v[70:71]
	v_fma_f64 v[22:23], v[30:31], v[34:35], -v[22:23]
	v_lshl_add_u64 v[28:29], v[28:29], 0, v[72:73]
	v_lshl_add_u64 v[30:31], v[26:27], 0, v[74:75]
	ds_write_b128 v217, v[42:45]
	ds_write_b128 v218, v[46:49]
	ds_write_b128 v219, v[50:53]
	ds_write_b128 v220, v[54:57] offset:25600
	ds_write_b128 v220, v[58:61] offset:34816
	s_lshl_b32 s62, s2, 7
	v_lshl_add_u64 v[30:31], v[30:31], 0, v[76:77]
	global_load_dwordx4 v[156:159], v[28:29], off
	global_load_dwordx4 v[160:163], v[30:31], off
	v_lshl_add_u64 v[26:27], v[26:27], 0, v[78:79]
	v_lshl_add_u64 v[28:29], v[68:69], 0, s[62:63]
	v_lshl_add_u64 v[26:27], v[26:27], 0, v[80:81]
	v_lshl_add_u64 v[28:29], v[28:29], 0, v[0:1]
	v_lshl_add_u64 v[30:31], v[28:29], 0, v[204:205]
	global_load_dwordx4 v[164:167], v[26:27], off
	global_load_dwordx4 v[168:171], v[30:31], off
	v_lshl_add_u64 v[26:27], v[28:29], 0, v[210:211]
	global_load_dwordx4 v[172:175], v[26:27], off
	v_cvt_f32_f64_e32 v23, v[22:23]
	v_sin_f32_e32 v22, v23
	v_cos_f32_e32 v24, v23
	v_sin_f32_e32 v23, v25
	v_cos_f32_e32 v25, v25
	v_mul_f64 v[28:29], v[20:21], v[34:35]
	v_floor_f64_e32 v[28:29], v[28:29]
	v_pk_mul_f32 v[26:27], v[6:7], v[22:23]
	v_fma_f64 v[20:21], v[20:21], v[34:35], -v[28:29]
	v_pk_fma_f32 v[26:27], v[2:3], v[24:25], v[26:27] neg_lo:[0,0,1] neg_hi:[0,0,1]
	v_pk_mul_f32 v[2:3], v[2:3], v[22:23]
	v_mul_f64 v[22:23], v[18:19], v[34:35]
	v_floor_f64_e32 v[22:23], v[22:23]
	v_fma_f64 v[18:19], v[18:19], v[34:35], -v[22:23]
	v_cvt_f32_f64_e32 v19, v[18:19]
	v_cvt_f32_f64_e32 v20, v[20:21]
	v_pk_mul_f32 v[16:17], v[16:17], s[54:55] op_sel_hi:[1,0]
	v_sin_f32_e32 v18, v19
	v_cos_f32_e32 v22, v19
	v_sin_f32_e32 v19, v20
	v_pk_fma_f32 v[2:3], v[6:7], v[24:25], v[2:3]
	v_cos_f32_e32 v23, v20
	v_pk_mul_f32 v[2:3], v[2:3], s[54:55] op_sel_hi:[1,0]
	v_cvt_pk_bf16_f32 v176, v16, v17
	v_or_b32_e32 v16, 0x11000, v0
	v_lshlrev_b32_e32 v0, 5, v221
	v_cvt_pk_bf16_f32 v182, v2, v3
	v_or_b32_e32 v2, v0, v38
	v_mul_lo_u32 v17, v2, s3
	v_mul_u32_u24_e32 v2, 0x90, v38
	v_pk_mul_f32 v[6:7], v[8:9], v[18:19]
	v_lshl_or_b32 v223, v40, 3, v2
	v_or_b32_e32 v2, v39, v38
	v_pk_fma_f32 v[6:7], v[4:5], v[22:23], v[6:7] neg_lo:[0,0,1] neg_hi:[0,0,1]
	v_pk_mul_f32 v[4:5], v[4:5], v[18:19]
	v_sub_u32_e32 v2, v2, v216
	v_pk_mul_f32 v[14:15], v[14:15], s[54:55] op_sel_hi:[1,0]
	v_pk_fma_f32 v[4:5], v[8:9], v[22:23], v[4:5]
	v_add_u32_e32 v224, 0x5f, v0
	v_sub_u32_e32 v0, v2, v0
	s_lshl_b32 s2, s8, 7
	v_pk_mul_f32 v[12:13], v[12:13], s[54:55] op_sel_hi:[1,0]
	v_pk_mul_f32 v[10:11], v[10:11], s[54:55] op_sel_hi:[1,0]
	v_pk_mul_f32 v[26:27], v[26:27], s[54:55] op_sel_hi:[1,0]
	v_pk_mul_f32 v[6:7], v[6:7], s[54:55] op_sel_hi:[1,0]
	v_pk_mul_f32 v[4:5], v[4:5], s[54:55] op_sel_hi:[1,0]
	v_cvt_pk_bf16_f32 v177, v14, v15
	v_lshlrev_b32_e32 v18, 4, v40
	v_add_u32_e32 v19, 0x11000, v223
	v_subrev_u32_e32 v0, s2, v0
	v_mov_b32_e32 v14, v1
	v_mov_b32_e32 v15, v1
	v_cvt_pk_bf16_f32 v135, v64, v65
	v_cvt_pk_bf16_f32 v178, v26, v27
	v_cvt_pk_bf16_f32 v179, v6, v7
	v_cvt_pk_bf16_f32 v180, v12, v13
	v_cvt_pk_bf16_f32 v181, v10, v11
	v_cvt_pk_bf16_f32 v183, v4, v5
	v_add_u32_e32 v225, 0x3f40, v0
	v_mov_b32_e32 v0, v1
	v_mov_b32_e32 v2, v1
	v_mov_b32_e32 v3, v1
	v_mov_b32_e32 v4, v1
	v_mov_b32_e32 v5, v1
	v_mov_b32_e32 v6, v1
	v_mov_b32_e32 v7, v1
	v_mov_b32_e32 v8, v1
	v_mov_b32_e32 v9, v1
	v_mov_b32_e32 v10, v1
	v_mov_b32_e32 v11, v1
	v_mov_b32_e32 v12, v1
	v_mov_b32_e32 v13, v1
	v_add_u32_e32 v226, v16, v32
	v_add_u32_e32 v227, v19, v222
	v_add_u32_e32 v228, v17, v18
	v_mov_b64_e32 v[30:31], v[14:15]
	v_mov_b64_e32 v[46:47], v[14:15]
	v_mov_b64_e32 v[62:63], v[14:15]
	v_mov_b64_e32 v[78:79], v[14:15]
	v_cvt_pk_bf16_f32 v103, v94, v95
	v_mov_b64_e32 v[28:29], v[12:13]
	v_mov_b64_e32 v[26:27], v[10:11]
	v_mov_b64_e32 v[24:25], v[8:9]
	v_mov_b64_e32 v[22:23], v[6:7]
	v_mov_b64_e32 v[20:21], v[4:5]
	v_mov_b64_e32 v[18:19], v[2:3]
	v_mov_b64_e32 v[16:17], v[0:1]
	v_mov_b64_e32 v[44:45], v[12:13]
	v_mov_b64_e32 v[42:43], v[10:11]
	v_mov_b64_e32 v[40:41], v[8:9]
	v_mov_b64_e32 v[38:39], v[6:7]
	v_mov_b64_e32 v[36:37], v[4:5]
	v_mov_b64_e32 v[34:35], v[2:3]
	v_mov_b64_e32 v[32:33], v[0:1]
	v_mov_b64_e32 v[60:61], v[12:13]
	v_mov_b64_e32 v[58:59], v[10:11]
	v_mov_b64_e32 v[56:57], v[8:9]
	v_mov_b64_e32 v[54:55], v[6:7]
	v_mov_b64_e32 v[52:53], v[4:5]
	v_mov_b64_e32 v[50:51], v[2:3]
	v_mov_b64_e32 v[48:49], v[0:1]
	v_mov_b64_e32 v[76:77], v[12:13]
	v_mov_b64_e32 v[74:75], v[10:11]
	v_mov_b64_e32 v[72:73], v[8:9]
	v_mov_b64_e32 v[70:71], v[6:7]
	v_mov_b64_e32 v[68:69], v[4:5]
	v_mov_b64_e32 v[66:67], v[2:3]
	v_mov_b64_e32 v[64:65], v[0:1]
	s_waitcnt lgkmcnt(0)
	s_barrier
	s_branch .LBB0_644

; #define AT_LOAD(RK, RV, T) { const size_t ko_ = (size_t)(T) * 64 * 192; const int vo_ = (T) * 64; \
;     _Pragma("unroll") for (int i = 0; i < 3; ++i) { const int id = tid + NT * i, row = id / 24, cc = id % 24; RK[i] = *(const u32x4*)(Kg + ko_ + row * 192 + cc * 8); } \
;     _Pragma("unroll") for (int i = 0; i < 2; ++i) RV[i] = *(const u32x4*)(Vg + (size_t)(vrow + 64 * i) * S_ + vo_ + vcc * 8); }
; #define AT_WRITE(RK, RV, ST) { char* dK = smem + (ST) * STG; \
;     _Pragma("unroll") for (int i = 0; i < 3; ++i) { const int id = tid + NT * i, row = id / 24, cc = id % 24; *(u32x4*)(dK + row * 400 + cc * 16) = RK[i]; } \
;     _Pragma("unroll") for (int i = 0; i < 2; ++i) *(u32x4*)(dK + KST + (vrow + 64 * i) * 144 + vcc * 16) = RV[i]; }
; DI void mla_attn_item(const Params& P, int hd, int b, char* smem) {
;     ...
;     AT_WRITE(rk1, rv1, 1);
;     AT_LOAD(rk1, rv1, (kt + 3 < ntl ? kt + 3 : ntl));
;     AT_COMPUTE(0, kt);
.LBB0_644:
	s_add_i32 s2, s60, 5
	s_min_u32 s2, s2, s57
	s_mul_i32 s62, s2, 0x6000
	v_lshl_add_u64 v[2:3], v[188:189], 0, s[62:63]
	v_lshl_add_u64 v[4:5], v[190:191], 1, v[2:3]
	s_waitcnt vmcnt(5)
	ds_write_b128 v217, v[136:139] offset:44032
	ds_write_b128 v218, v[140:143] offset:44032
	ds_write_b128 v219, v[144:147] offset:44032
	ds_write_b128 v226, v[148:151]
	ds_write_b128 v226, v[152:155] offset:9216
	v_lshl_add_u64 v[4:5], v[192:193], 1, v[4:5]
	v_lshl_add_u64 v[6:7], v[194:195], 1, v[2:3]
	v_lshl_add_u64 v[2:3], v[198:199], 1, v[2:3]
	s_lshl_b32 s62, s2, 7
	v_lshl_add_u64 v[6:7], v[196:197], 1, v[6:7]
	global_load_dwordx4 v[136:139], v[4:5], off
	global_load_dwordx4 v[140:143], v[6:7], off
	v_lshl_add_u64 v[2:3], v[200:201], 1, v[2:3]
	v_lshl_add_u64 v[4:5], v[202:203], 0, s[62:63]
	v_lshl_add_u64 v[6:7], v[4:5], 0, v[204:205]
	global_load_dwordx4 v[144:147], v[2:3], off
	global_load_dwordx4 v[148:151], v[6:7], off
	v_lshl_add_u64 v[2:3], v[4:5], 0, v[210:211]
	global_load_dwordx4 v[152:155], v[2:3], off
	v_add_u32_e32 v0, 0xffffffa1, v224
	v_cmp_le_i32_e32 vcc, v0, v213
	s_and_saveexec_b64 s[38:39], vcc
	s_cbranch_execz .LBB0_650
	s_setprio 1
	ds_read_b128 v[2:5], v228
	ds_read_b128 v[230:233], v228 offset:32
	ds_read_b128 v[234:237], v228 offset:64
	ds_read_b128 v[246:249], v228 offset:96
	ds_read_b128 v[250:253], v228 offset:128
	s_waitcnt lgkmcnt(4)
	v_mfma_f32_32x32x16_bf16 v[80:95], v[2:5], v[96:99], 0
	ds_read_b128 v[2:5], v228 offset:160
	s_waitcnt lgkmcnt(4)
	v_mfma_f32_32x32x16_bf16 v[80:95], v[230:233], v[100:103], v[80:95]
	ds_read_b128 v[230:233], v228 offset:192
	s_waitcnt lgkmcnt(4)
	v_mfma_f32_32x32x16_bf16 v[80:95], v[234:237], v[104:107], v[80:95]
	ds_read_b128 v[234:237], v228 offset:224
	s_waitcnt lgkmcnt(4)
	v_mfma_f32_32x32x16_bf16 v[80:95], v[246:249], v[108:111], v[80:95]
	ds_read_b128 v[246:249], v228 offset:256
	s_waitcnt lgkmcnt(4)
	v_mfma_f32_32x32x16_bf16 v[80:95], v[250:253], v[112:115], v[80:95]
	ds_read_b128 v[250:253], v228 offset:288
	s_waitcnt lgkmcnt(4)
	v_mfma_f32_32x32x16_bf16 v[80:95], v[2:5], v[116:119], v[80:95]
	ds_read_b128 v[2:5], v228 offset:320
	s_waitcnt lgkmcnt(4)
	v_mfma_f32_32x32x16_bf16 v[80:95], v[230:233], v[120:123], v[80:95]
	ds_read_b128 v[230:233], v228 offset:352
	s_waitcnt lgkmcnt(4)
	v_mfma_f32_32x32x16_bf16 v[80:95], v[234:237], v[124:127], v[80:95]
	s_waitcnt lgkmcnt(3)
	v_mfma_f32_32x32x16_bf16 v[80:95], v[246:249], v[128:131], v[80:95]
	s_waitcnt lgkmcnt(2)
	v_mfma_f32_32x32x16_bf16 v[80:95], v[250:253], v[176:179], v[80:95]
	s_waitcnt lgkmcnt(1)
	v_mfma_f32_32x32x16_bf16 v[80:95], v[2:5], v[132:135], v[80:95]
	s_waitcnt lgkmcnt(0)
	v_mfma_f32_32x32x16_bf16 v[80:95], v[230:233], v[180:183], v[80:95]
	s_setprio 0
	v_subrev_u32_e32 v0, 64, v224
	v_cmp_gt_i32_e32 vcc, v0, v213
	s_and_saveexec_b64 s[78:79], vcc
	s_cbranch_execz .LBB0_647
	v_add_u32_e32 v0, 64, v225
	s_nop 0
	v_cmp_gt_i32_e64 s[30:31], 26, v0
	v_cmp_gt_i32_e64 s[34:35], 27, v0
	v_cmp_gt_i32_e64 s[28:29], 25, v0
	s_and_b64 s[30:31], s[34:35], s[30:31]
	v_cmp_gt_i32_e64 s[26:27], 24, v0
	s_and_b64 s[28:29], s[30:31], s[28:29]
	v_cmp_gt_i32_e64 s[24:25], 19, v0
	s_and_b64 s[26:27], s[28:29], s[26:27]
	v_cmp_gt_i32_e64 s[22:23], 18, v0
	s_and_b64 s[24:25], s[26:27], s[24:25]
	v_cmp_gt_i32_e64 s[20:21], 17, v0
	s_and_b64 s[22:23], s[24:25], s[22:23]
	v_cmp_gt_i32_e64 s[18:19], 16, v0
	s_and_b64 s[20:21], s[22:23], s[20:21]
	v_cmp_gt_i32_e64 s[16:17], 11, v0
	s_and_b64 s[18:19], s[20:21], s[18:19]
	v_cmp_gt_i32_e64 s[14:15], 10, v0
	s_and_b64 s[16:17], s[18:19], s[16:17]
	v_cmp_gt_i32_e64 s[12:13], 9, v0
	s_and_b64 s[14:15], s[16:17], s[14:15]
	v_cmp_gt_i32_e64 s[10:11], 8, v0
	s_and_b64 s[12:13], s[14:15], s[12:13]
	v_cmp_gt_i32_e64 s[8:9], 3, v0
	s_and_b64 s[10:11], s[12:13], s[10:11]
	v_cmp_gt_i32_e64 s[4:5], 2, v0
	s_and_b64 s[8:9], s[10:11], s[8:9]
	v_cmp_gt_i32_e64 s[2:3], 1, v0
	s_and_b64 s[4:5], s[8:9], s[4:5]
	v_cmp_gt_i32_e32 vcc, 0, v0
	s_and_b64 s[2:3], s[4:5], s[2:3]
	s_and_b64 vcc, s[2:3], vcc
	v_cndmask_b32_e64 v95, v95, v244, s[34:35]
	v_cndmask_b32_e64 v94, v94, v244, s[30:31]
	v_cndmask_b32_e64 v93, v93, v244, s[28:29]
	v_cndmask_b32_e64 v92, v92, v244, s[26:27]
	v_cndmask_b32_e64 v91, v91, v244, s[24:25]
	v_cndmask_b32_e64 v90, v90, v244, s[22:23]
	v_cndmask_b32_e64 v89, v89, v244, s[20:21]
	v_cndmask_b32_e64 v88, v88, v244, s[18:19]
	v_cndmask_b32_e64 v87, v87, v244, s[16:17]
	v_cndmask_b32_e64 v86, v86, v244, s[14:15]
	v_cndmask_b32_e64 v85, v85, v244, s[12:13]
	v_cndmask_b32_e64 v84, v84, v244, s[10:11]
	v_cndmask_b32_e64 v83, v83, v244, s[8:9]
	v_cndmask_b32_e64 v82, v82, v244, s[4:5]
	v_cndmask_b32_e64 v81, v81, v244, s[2:3]
	v_cndmask_b32_e32 v80, v80, v244, vcc

; #define AT_LOAD(RK, RV, T) { const size_t ko_ = (size_t)(T) * 64 * 192; const int vo_ = (T) * 64; \
;     _Pragma("unroll") for (int i = 0; i < 3; ++i) { const int id = tid + NT * i, row = id / 24, cc = id % 24; RK[i] = *(const u32x4*)(Kg + ko_ + row * 192 + cc * 8); } \
;     _Pragma("unroll") for (int i = 0; i < 2; ++i) RV[i] = *(const u32x4*)(Vg + (size_t)(vrow + 64 * i) * S_ + vo_ + vcc * 8); }
; #define AT_WRITE(RK, RV, ST) { char* dK = smem + (ST) * STG; \
;     _Pragma("unroll") for (int i = 0; i < 3; ++i) { const int id = tid + NT * i, row = id / 24, cc = id % 24; *(u32x4*)(dK + row * 400 + cc * 16) = RK[i]; } \
;     _Pragma("unroll") for (int i = 0; i < 2; ++i) *(u32x4*)(dK + KST + (vrow + 64 * i) * 144 + vcc * 16) = RV[i]; }
; DI void mla_attn_item(const Params& P, int hd, int b, char* smem) {
;     ...
;     AT_WRITE(rk0, rv0, 0);
;     AT_LOAD(rk0, rv0, (kt + 4 < ntl ? kt + 4 : ntl));
;     AT_COMPUTE(1, kt + 1);
.LBB0_650:
	s_or_b64 exec, exec, s[38:39]
	s_add_i32 s2, s60, 6
	s_min_u32 s2, s2, s57
	s_mul_i32 s62, s2, 0x6000
	v_lshl_add_u64 v[2:3], v[188:189], 0, s[62:63]
	v_lshl_add_u64 v[4:5], v[190:191], 1, v[2:3]
	s_waitcnt lgkmcnt(0)
	s_barrier
	s_waitcnt vmcnt(5)
	ds_write_b128 v217, v[156:159]
	ds_write_b128 v218, v[160:163]
	ds_write_b128 v219, v[164:167]
	ds_write_b128 v220, v[168:171] offset:25600
	ds_write_b128 v220, v[172:175] offset:34816
	v_lshl_add_u64 v[4:5], v[192:193], 1, v[4:5]
	v_lshl_add_u64 v[6:7], v[194:195], 1, v[2:3]
	v_lshl_add_u64 v[2:3], v[198:199], 1, v[2:3]
	s_lshl_b32 s62, s2, 7
	v_lshl_add_u64 v[6:7], v[196:197], 1, v[6:7]
	global_load_dwordx4 v[156:159], v[4:5], off
	global_load_dwordx4 v[160:163], v[6:7], off
	v_lshl_add_u64 v[2:3], v[200:201], 1, v[2:3]
	v_lshl_add_u64 v[4:5], v[202:203], 0, s[62:63]
	v_lshl_add_u64 v[6:7], v[4:5], 0, v[204:205]
	global_load_dwordx4 v[164:167], v[2:3], off
	global_load_dwordx4 v[168:171], v[6:7], off
	v_lshl_add_u64 v[2:3], v[4:5], 0, v[210:211]
	global_load_dwordx4 v[172:175], v[2:3], off
	v_subrev_u32_e32 v0, 31, v224
	v_cmp_le_i32_e32 vcc, v0, v213
	s_and_saveexec_b64 s[38:39], vcc
	s_cbranch_execz .LBB0_643
	s_setprio 1
	ds_read_b128 v[2:5], v228 offset:44032
	ds_read_b128 v[230:233], v228 offset:44064
	ds_read_b128 v[234:237], v228 offset:44096
	ds_read_b128 v[246:249], v228 offset:44128
	ds_read_b128 v[250:253], v228 offset:44160
	s_waitcnt lgkmcnt(4)
	v_mfma_f32_32x32x16_bf16 v[80:95], v[2:5], v[96:99], 0
	ds_read_b128 v[2:5], v228 offset:44192
	s_waitcnt lgkmcnt(4)
	v_mfma_f32_32x32x16_bf16 v[80:95], v[230:233], v[100:103], v[80:95]
	ds_read_b128 v[230:233], v228 offset:44224
	s_waitcnt lgkmcnt(4)
	v_mfma_f32_32x32x16_bf16 v[80:95], v[234:237], v[104:107], v[80:95]
	ds_read_b128 v[234:237], v228 offset:44256
	s_waitcnt lgkmcnt(4)
	v_mfma_f32_32x32x16_bf16 v[80:95], v[246:249], v[108:111], v[80:95]
	ds_read_b128 v[246:249], v228 offset:44288
	s_waitcnt lgkmcnt(4)
	v_mfma_f32_32x32x16_bf16 v[80:95], v[250:253], v[112:115], v[80:95]
	ds_read_b128 v[250:253], v228 offset:44320
	s_waitcnt lgkmcnt(4)
	v_mfma_f32_32x32x16_bf16 v[80:95], v[2:5], v[116:119], v[80:95]
	ds_read_b128 v[2:5], v228 offset:44352
	s_waitcnt lgkmcnt(4)
	v_mfma_f32_32x32x16_bf16 v[80:95], v[230:233], v[120:123], v[80:95]
	ds_read_b128 v[230:233], v228 offset:44384
	s_waitcnt lgkmcnt(4)
	v_mfma_f32_32x32x16_bf16 v[80:95], v[234:237], v[124:127], v[80:95]
	s_waitcnt lgkmcnt(3)
	v_mfma_f32_32x32x16_bf16 v[80:95], v[246:249], v[128:131], v[80:95]
	s_waitcnt lgkmcnt(2)
	v_mfma_f32_32x32x16_bf16 v[80:95], v[250:253], v[176:179], v[80:95]
	s_waitcnt lgkmcnt(1)
	v_mfma_f32_32x32x16_bf16 v[80:95], v[2:5], v[132:135], v[80:95]
	s_waitcnt lgkmcnt(0)
	v_mfma_f32_32x32x16_bf16 v[80:95], v[230:233], v[180:183], v[80:95]
	s_setprio 0
	v_cmp_gt_i32_e32 vcc, v224, v213
	s_and_saveexec_b64 s[78:79], vcc
	s_cbranch_execz .LBB0_653
	v_mov_b32_e32 v0, v225
	s_nop 0
	v_cmp_gt_i32_e64 s[30:31], 26, v0
	v_cmp_gt_i32_e64 s[34:35], 27, v0
	v_cmp_gt_i32_e64 s[28:29], 25, v0
	s_and_b64 s[30:31], s[34:35], s[30:31]
	v_cmp_gt_i32_e64 s[26:27], 24, v0
	s_and_b64 s[28:29], s[30:31], s[28:29]
	v_cmp_gt_i32_e64 s[24:25], 19, v0
	s_and_b64 s[26:27], s[28:29], s[26:27]
	v_cmp_gt_i32_e64 s[22:23], 18, v0
	s_and_b64 s[24:25], s[26:27], s[24:25]
	v_cmp_gt_i32_e64 s[20:21], 17, v0
	s_and_b64 s[22:23], s[24:25], s[22:23]
	v_cmp_gt_i32_e64 s[18:19], 16, v0
	s_and_b64 s[20:21], s[22:23], s[20:21]
	v_cmp_gt_i32_e64 s[16:17], 11, v0
	s_and_b64 s[18:19], s[20:21], s[18:19]
	v_cmp_gt_i32_e64 s[14:15], 10, v0
	s_and_b64 s[16:17], s[18:19], s[16:17]
	v_cmp_gt_i32_e64 s[12:13], 9, v0
	s_and_b64 s[14:15], s[16:17], s[14:15]
	v_cmp_gt_i32_e64 s[10:11], 8, v0
	s_and_b64 s[12:13], s[14:15], s[12:13]
	v_cmp_gt_i32_e64 s[8:9], 3, v0
	s_and_b64 s[10:11], s[12:13], s[10:11]
	v_cmp_gt_i32_e64 s[4:5], 2, v0
	s_and_b64 s[8:9], s[10:11], s[8:9]
	v_cmp_gt_i32_e64 s[2:3], 1, v0
	s_and_b64 s[4:5], s[8:9], s[4:5]
	v_cmp_gt_i32_e32 vcc, 0, v0
	s_and_b64 s[2:3], s[4:5], s[2:3]
	s_and_b64 vcc, s[2:3], vcc
	v_cndmask_b32_e64 v95, v95, v244, s[34:35]
	v_cndmask_b32_e64 v94, v94, v244, s[30:31]
	v_cndmask_b32_e64 v93, v93, v244, s[28:29]
	v_cndmask_b32_e64 v92, v92, v244, s[26:27]
	v_cndmask_b32_e64 v91, v91, v244, s[24:25]
	v_cndmask_b32_e64 v90, v90, v244, s[22:23]
	v_cndmask_b32_e64 v89, v89, v244, s[20:21]
	v_cndmask_b32_e64 v88, v88, v244, s[18:19]
	v_cndmask_b32_e64 v87, v87, v244, s[16:17]
	v_cndmask_b32_e64 v86, v86, v244, s[14:15]
	v_cndmask_b32_e64 v85, v85, v244, s[12:13]
	v_cndmask_b32_e64 v84, v84, v244, s[10:11]
	v_cndmask_b32_e64 v83, v83, v244, s[8:9]
	v_cndmask_b32_e64 v82, v82, v244, s[4:5]
	v_cndmask_b32_e64 v81, v81, v244, s[2:3]
	v_cndmask_b32_e32 v80, v80, v244, vcc

.LBB0_674:
	s_or_b64 exec, exec, s[10:11]
	v_mul_f32_e32 v140, v119, v140
	v_lshlrev_b32_e32 v144, 16, v132
	v_mul_f32_e32 v140, v140, v144
	v_cvt_pk_bf16_f32 v140, v140, s0
	v_add_u32_e32 v144, v166, v159
	ds_write_b16 v144, v140
	v_mul_f32_e32 v140, v119, v141
	v_and_b32_e32 v132, 0xffff0000, v132
	v_mul_f32_e32 v132, v140, v132
	v_cvt_pk_bf16_f32 v132, v132, s0
	ds_write_b16 v144, v132 offset:128
	v_mul_f32_e32 v132, v119, v138
	v_lshlrev_b32_e32 v138, 16, v133
	v_mul_f32_e32 v132, v132, v138
	v_cvt_pk_bf16_f32 v132, v132, s0
	ds_write_b16 v144, v132 offset:256
	v_mul_f32_e32 v132, v119, v139
	v_and_b32_e32 v133, 0xffff0000, v133
	v_mul_f32_e32 v132, v132, v133
	s_min_u32 s10, s12, 0xfd
	v_cvt_pk_bf16_f32 v132, v132, s0
	s_lshl_b32 s62, s10, 14
	ds_write_b16 v144, v132 offset:384
	v_lshl_add_u64 v[132:133], v[116:117], 0, s[62:63]
	v_lshl_add_u64 v[132:133], v[132:133], 0, v[0:1]
	s_mov_b32 s10, 0x8000
	v_lshl_add_u64 v[146:147], v[132:133], 0, s[76:77]
	v_add_co_u32_e32 v132, vcc, s10, v132
	s_add_u32 s4, s4, 0x8000
	s_nop 0
	v_addc_co_u32_e32 v133, vcc, 0, v133, vcc
	global_load_dwordx2 v[144:145], v[132:133], off nt
	global_load_dwordx2 v[140:141], v[146:147], off offset:32 nt
	global_load_dwordx2 v[138:139], v[146:147], off offset:64 nt
	s_nop 0
	global_load_dwordx2 v[132:133], v[146:147], off offset:96 nt
	s_addc_u32 s5, s5, 0
	s_cmpk_gt_u32 s12, 0xfd
	s_waitcnt lgkmcnt(0)
	s_barrier
	s_cbranch_scc1 .LBB0_693
.LBB0_675:
	s_add_i32 s12, s12, 2
	s_min_u32 s10, s12, 0xfc
	s_lshl_b32 s10, s10, 13
	s_waitcnt vmcnt(22)
	ds_write_b128 v118, v[6:9] offset:62464
	v_add_u32_e32 v6, 0x13800, v118
	s_add_i32 s62, s10, 0x6000
	ds_write_b128 v6, v[2:5]
	v_add_u32_e32 v2, 0x17c00, v120
	s_lshl_b32 s10, s62, 1
	s_mov_b32 s11, s63
	ds_write_b128 v2, v[10:13]
	ds_write_b128 v164, v[14:17] offset:4352
	ds_write_b128 v6, v[18:21] offset:4352
	ds_write_b128 v2, v[22:25] offset:4608
	ds_write_b128 v164, v[26:29] offset:8704
	ds_write_b128 v6, v[30:33] offset:8704
	ds_write_b128 v2, v[34:37] offset:9216
	ds_write_b128 v164, v[38:41] offset:13056
	ds_write_b128 v6, v[58:61] offset:13056
	ds_write_b128 v2, v[62:65] offset:13824
	v_lshl_add_u64 v[34:35], v[124:125], 0, s[10:11]
	v_add_co_u32_e32 v14, vcc, s82, v34
	v_lshl_add_u64 v[58:59], v[126:127], 0, s[10:11]
	s_nop 0
	v_addc_co_u32_e32 v15, vcc, 0, v35, vcc
	v_add_co_u32_e32 v18, vcc, s82, v58
	v_lshl_add_u64 v[60:61], v[128:129], 0, s[10:11]
	s_nop 0
	v_addc_co_u32_e32 v19, vcc, 0, v59, vcc
	v_add_co_u32_e32 v22, vcc, s82, v60
	v_add_u32_e32 v2, 0x1c400, v120
	s_nop 0
	v_addc_co_u32_e32 v23, vcc, 0, v61, vcc
	v_add_co_u32_e32 v26, vcc, s83, v34
	ds_write_b128 v2, v[74:77]
	ds_write_b128 v2, v[78:81] offset:4608
	v_addc_co_u32_e32 v27, vcc, 0, v35, vcc
	v_add_co_u32_e32 v30, vcc, s83, v58
	global_load_dwordx4 v[6:9], v[34:35], off nt
	global_load_dwordx4 v[2:5], v[58:59], off nt
	v_addc_co_u32_e32 v31, vcc, 0, v59, vcc
	v_add_co_u32_e32 v36, vcc, s83, v60
	v_lshl_add_u64 v[74:75], v[130:131], 0, s[62:63]
	s_nop 0
	v_addc_co_u32_e32 v37, vcc, 0, v61, vcc
	v_add_co_u32_e32 v38, vcc, 0x3000, v34
	global_load_dwordx4 v[10:13], v[60:61], off nt
	s_nop 0
	global_load_dwordx4 v[14:17], v[14:15], off nt
	v_addc_co_u32_e32 v39, vcc, 0, v35, vcc
	v_add_co_u32_e32 v58, vcc, 0x3000, v58
	global_load_dwordx4 v[18:21], v[18:19], off nt
	s_nop 0
	global_load_dwordx4 v[22:25], v[22:23], off nt
	v_addc_co_u32_e32 v59, vcc, 0, v59, vcc
	v_add_co_u32_e32 v62, vcc, 0x3000, v60
	global_load_dwordx4 v[26:29], v[26:27], off nt
	s_nop 0
	global_load_dwordx4 v[30:33], v[30:31], off nt
	v_addc_co_u32_e32 v63, vcc, 0, v61, vcc
	v_add_co_u32_e32 v78, vcc, 0x1000, v74
	global_load_dwordx4 v[34:37], v[36:37], off nt
	s_nop 0
	global_load_dwordx4 v[38:41], v[38:39], off nt
	v_addc_co_u32_e32 v79, vcc, 0, v75, vcc
	global_load_dwordx4 v[58:61], v[58:59], off nt
	s_nop 0
	global_load_dwordx4 v[62:65], v[62:63], off nt
	s_nop 0
	global_load_dwordx4 v[74:77], v[74:75], off nt
	s_nop 0
	global_load_dwordx4 v[78:81], v[78:79], off nt
	s_cmp_lg_u32 s4, 0
	s_cbranch_scc0 .LBB0_685
	s_waitcnt vmcnt(32)
	v_add_u32_e32 v169, v165, v158
	ds_read_b64 v[146:147], v169
	s_waitcnt lgkmcnt(0)
	v_lshlrev_b32_e32 v148, 16, v146
	v_and_b32_e32 v149, 0xffff0000, v146
	v_lshlrev_b32_e32 v146, 16, v147
	v_and_b32_e32 v147, 0xffff0000, v147
	v_pk_mul_f32 v[154:155], v[146:147], v[146:147]
	v_pk_mul_f32 v[150:151], v[148:149], v[148:149]
	s_nop 0
	v_mov_b32_dpp v154, v154 quad_perm:[1,0,3,2] row_mask:0xf bank_mask:0xf bound_ctrl:1
	v_mov_b32_dpp v150, v150 quad_perm:[1,0,3,2] row_mask:0xf bank_mask:0xf bound_ctrl:1
	v_mov_b32_dpp v151, v151 quad_perm:[1,0,3,2] row_mask:0xf bank_mask:0xf bound_ctrl:1
	v_mov_b32_dpp v155, v155 quad_perm:[1,0,3,2] row_mask:0xf bank_mask:0xf bound_ctrl:1
	v_pk_fma_f32 v[150:151], v[148:149], v[148:149], v[150:151]
	v_pk_fma_f32 v[154:155], v[146:147], v[146:147], v[154:155]
	s_nop 0
	v_mov_b32_dpp v152, v150 quad_perm:[2,3,0,1] row_mask:0xf bank_mask:0xf bound_ctrl:1
	v_mov_b32_dpp v153, v151 quad_perm:[2,3,0,1] row_mask:0xf bank_mask:0xf bound_ctrl:1
	v_mov_b32_dpp v156, v154 quad_perm:[2,3,0,1] row_mask:0xf bank_mask:0xf bound_ctrl:1
	v_mov_b32_dpp v157, v155 quad_perm:[2,3,0,1] row_mask:0xf bank_mask:0xf bound_ctrl:1
	v_pk_add_f32 v[150:151], v[150:151], v[152:153]
	v_pk_add_f32 v[154:155], v[154:155], v[156:157]
	s_nop 0
	v_mov_b32_dpp v152, v150 row_half_mirror row_mask:0xf bank_mask:0xf bound_ctrl:1
	v_mov_b32_dpp v153, v151 row_half_mirror row_mask:0xf bank_mask:0xf bound_ctrl:1
	v_mov_b32_dpp v156, v154 row_half_mirror row_mask:0xf bank_mask:0xf bound_ctrl:1
	v_mov_b32_dpp v157, v155 row_half_mirror row_mask:0xf bank_mask:0xf bound_ctrl:1
	v_pk_add_f32 v[150:151], v[150:151], v[152:153]
	v_pk_add_f32 v[154:155], v[154:155], v[156:157]
	s_nop 0
	v_mov_b32_dpp v152, v150 row_mirror row_mask:0xf bank_mask:0xf bound_ctrl:1
	v_mov_b32_dpp v153, v151 row_mirror row_mask:0xf bank_mask:0xf bound_ctrl:1
	v_mov_b32_dpp v156, v154 row_mirror row_mask:0xf bank_mask:0xf bound_ctrl:1
	v_mov_b32_dpp v157, v155 row_mirror row_mask:0xf bank_mask:0xf bound_ctrl:1
	s_and_saveexec_b64 s[10:11], s[2:3]
	v_pk_add_f32 v[154:155], v[154:155], v[156:157]
	v_pk_add_f32 v[152:153], v[150:151], v[152:153]
	ds_write_b128 v160, v[152:155]
	s_or_b64 exec, exec, s[10:11]
	v_mul_f32_e32 v148, v119, v148
	v_lshlrev_b32_e32 v150, 16, v142
	v_mul_f32_e32 v148, v148, v150
	v_cvt_pk_bf16_f32 v148, v148, s0
	v_add_u32_e32 v150, v121, v163
	ds_write_b16 v150, v148
	v_mul_f32_e32 v148, v119, v149
	v_and_b32_e32 v142, 0xffff0000, v142
	v_mul_f32_e32 v142, v148, v142
	v_cvt_pk_bf16_f32 v142, v142, s0
	ds_write_b16 v150, v142 offset:128
	v_mul_f32_e32 v142, v119, v146
	v_lshlrev_b32_e32 v146, 16, v143
	v_mul_f32_e32 v142, v142, v146
	v_cvt_pk_bf16_f32 v142, v142, s0
	ds_write_b16 v150, v142 offset:256
	v_mul_f32_e32 v142, v119, v147
	v_and_b32_e32 v143, 0xffff0000, v143
	v_mul_f32_e32 v142, v142, v143
	v_cvt_pk_bf16_f32 v142, v142, s0
	ds_write_b16 v150, v142 offset:384
	ds_read_b64 v[142:143], v169 offset:512
	s_waitcnt lgkmcnt(0)
	v_lshlrev_b32_e32 v146, 16, v142
	v_and_b32_e32 v147, 0xffff0000, v142
	v_lshlrev_b32_e32 v142, 16, v143
	v_and_b32_e32 v143, 0xffff0000, v143
	v_pk_mul_f32 v[152:153], v[142:143], v[142:143]
	v_pk_mul_f32 v[148:149], v[146:147], v[146:147]
	s_nop 0
	v_mov_b32_dpp v152, v152 quad_perm:[1,0,3,2] row_mask:0xf bank_mask:0xf bound_ctrl:1
	v_mov_b32_dpp v148, v148 quad_perm:[1,0,3,2] row_mask:0xf bank_mask:0xf bound_ctrl:1
	v_mov_b32_dpp v149, v149 quad_perm:[1,0,3,2] row_mask:0xf bank_mask:0xf bound_ctrl:1
	v_mov_b32_dpp v153, v153 quad_perm:[1,0,3,2] row_mask:0xf bank_mask:0xf bound_ctrl:1
	v_pk_fma_f32 v[148:149], v[146:147], v[146:147], v[148:149]
	v_pk_fma_f32 v[152:153], v[142:143], v[142:143], v[152:153]
	s_nop 0
	v_mov_b32_dpp v150, v148 quad_perm:[2,3,0,1] row_mask:0xf bank_mask:0xf bound_ctrl:1
	v_mov_b32_dpp v151, v149 quad_perm:[2,3,0,1] row_mask:0xf bank_mask:0xf bound_ctrl:1
	v_mov_b32_dpp v154, v152 quad_perm:[2,3,0,1] row_mask:0xf bank_mask:0xf bound_ctrl:1
	v_mov_b32_dpp v155, v153 quad_perm:[2,3,0,1] row_mask:0xf bank_mask:0xf bound_ctrl:1
	v_pk_add_f32 v[148:149], v[148:149], v[150:151]
	v_pk_add_f32 v[152:153], v[152:153], v[154:155]
	s_nop 0
	v_mov_b32_dpp v150, v148 row_half_mirror row_mask:0xf bank_mask:0xf bound_ctrl:1
	v_mov_b32_dpp v151, v149 row_half_mirror row_mask:0xf bank_mask:0xf bound_ctrl:1
	v_mov_b32_dpp v154, v152 row_half_mirror row_mask:0xf bank_mask:0xf bound_ctrl:1
	v_mov_b32_dpp v155, v153 row_half_mirror row_mask:0xf bank_mask:0xf bound_ctrl:1
	v_pk_add_f32 v[148:149], v[148:149], v[150:151]
	v_pk_add_f32 v[152:153], v[152:153], v[154:155]
	s_nop 0
	v_mov_b32_dpp v150, v148 row_mirror row_mask:0xf bank_mask:0xf bound_ctrl:1
	v_mov_b32_dpp v151, v149 row_mirror row_mask:0xf bank_mask:0xf bound_ctrl:1
	v_mov_b32_dpp v154, v152 row_mirror row_mask:0xf bank_mask:0xf bound_ctrl:1
	v_mov_b32_dpp v155, v153 row_mirror row_mask:0xf bank_mask:0xf bound_ctrl:1
	s_and_saveexec_b64 s[10:11], s[2:3]
	v_pk_add_f32 v[152:153], v[152:153], v[154:155]
	v_pk_add_f32 v[150:151], v[148:149], v[150:151]
	ds_write_b128 v160, v[150:153] offset:64
	s_or_b64 exec, exec, s[10:11]
	v_mul_f32_e32 v146, v119, v146
	v_lshlrev_b32_e32 v148, 16, v136
	v_mul_f32_e32 v146, v146, v148
	v_cvt_pk_bf16_f32 v146, v146, s0
	v_add_u32_e32 v148, v121, v162
	ds_write_b16 v148, v146
	v_mul_f32_e32 v146, v119, v147
	v_and_b32_e32 v136, 0xffff0000, v136
	v_mul_f32_e32 v136, v146, v136
	v_cvt_pk_bf16_f32 v136, v136, s0
	ds_write_b16 v148, v136 offset:128
	v_mul_f32_e32 v136, v119, v142
	v_lshlrev_b32_e32 v142, 16, v137
	v_mul_f32_e32 v136, v136, v142
	v_cvt_pk_bf16_f32 v136, v136, s0
	ds_write_b16 v148, v136 offset:256
	v_mul_f32_e32 v136, v119, v143
	v_and_b32_e32 v137, 0xffff0000, v137
	v_mul_f32_e32 v136, v136, v137
	v_cvt_pk_bf16_f32 v136, v136, s0
	ds_write_b16 v148, v136 offset:384
	ds_read_b64 v[136:137], v169 offset:1024
	s_waitcnt lgkmcnt(0)
	v_lshlrev_b32_e32 v142, 16, v136
	v_and_b32_e32 v143, 0xffff0000, v136
	v_lshlrev_b32_e32 v136, 16, v137
	v_and_b32_e32 v137, 0xffff0000, v137
	v_pk_mul_f32 v[150:151], v[136:137], v[136:137]
	v_pk_mul_f32 v[146:147], v[142:143], v[142:143]
	s_nop 0
	v_mov_b32_dpp v150, v150 quad_perm:[1,0,3,2] row_mask:0xf bank_mask:0xf bound_ctrl:1
	v_mov_b32_dpp v146, v146 quad_perm:[1,0,3,2] row_mask:0xf bank_mask:0xf bound_ctrl:1
	v_mov_b32_dpp v147, v147 quad_perm:[1,0,3,2] row_mask:0xf bank_mask:0xf bound_ctrl:1
	v_mov_b32_dpp v151, v151 quad_perm:[1,0,3,2] row_mask:0xf bank_mask:0xf bound_ctrl:1
	v_pk_fma_f32 v[146:147], v[142:143], v[142:143], v[146:147]
	v_pk_fma_f32 v[150:151], v[136:137], v[136:137], v[150:151]
	s_nop 0
	v_mov_b32_dpp v148, v146 quad_perm:[2,3,0,1] row_mask:0xf bank_mask:0xf bound_ctrl:1
	v_mov_b32_dpp v149, v147 quad_perm:[2,3,0,1] row_mask:0xf bank_mask:0xf bound_ctrl:1
	v_mov_b32_dpp v152, v150 quad_perm:[2,3,0,1] row_mask:0xf bank_mask:0xf bound_ctrl:1
	v_mov_b32_dpp v153, v151 quad_perm:[2,3,0,1] row_mask:0xf bank_mask:0xf bound_ctrl:1
	v_pk_add_f32 v[146:147], v[146:147], v[148:149]
	v_pk_add_f32 v[150:151], v[150:151], v[152:153]
	s_nop 0
	v_mov_b32_dpp v148, v146 row_half_mirror row_mask:0xf bank_mask:0xf bound_ctrl:1
	v_mov_b32_dpp v149, v147 row_half_mirror row_mask:0xf bank_mask:0xf bound_ctrl:1
	v_mov_b32_dpp v152, v150 row_half_mirror row_mask:0xf bank_mask:0xf bound_ctrl:1
	v_mov_b32_dpp v153, v151 row_half_mirror row_mask:0xf bank_mask:0xf bound_ctrl:1
	v_pk_add_f32 v[146:147], v[146:147], v[148:149]
	v_pk_add_f32 v[150:151], v[150:151], v[152:153]
	s_nop 0
	v_mov_b32_dpp v148, v146 row_mirror row_mask:0xf bank_mask:0xf bound_ctrl:1
	v_mov_b32_dpp v149, v147 row_mirror row_mask:0xf bank_mask:0xf bound_ctrl:1
	v_mov_b32_dpp v152, v150 row_mirror row_mask:0xf bank_mask:0xf bound_ctrl:1
	v_mov_b32_dpp v153, v151 row_mirror row_mask:0xf bank_mask:0xf bound_ctrl:1
	s_and_saveexec_b64 s[10:11], s[2:3]
	v_pk_add_f32 v[150:151], v[150:151], v[152:153]
	v_pk_add_f32 v[148:149], v[146:147], v[148:149]
	ds_write_b128 v160, v[148:151] offset:128
	s_or_b64 exec, exec, s[10:11]
	v_mul_f32_e32 v142, v119, v142
	v_lshlrev_b32_e32 v146, 16, v122
	v_mul_f32_e32 v142, v142, v146
	v_cvt_pk_bf16_f32 v142, v142, s0
	v_add_u32_e32 v146, v121, v161
	ds_write_b16 v146, v142
	v_mul_f32_e32 v142, v119, v143
	v_and_b32_e32 v122, 0xffff0000, v122
	v_mul_f32_e32 v122, v142, v122
	v_cvt_pk_bf16_f32 v122, v122, s0
	ds_write_b16 v146, v122 offset:128
	v_mul_f32_e32 v122, v119, v136
	v_lshlrev_b32_e32 v136, 16, v123
	v_mul_f32_e32 v122, v122, v136
	v_cvt_pk_bf16_f32 v122, v122, s0
	ds_write_b16 v146, v122 offset:256
	v_mul_f32_e32 v122, v119, v137
	v_and_b32_e32 v123, 0xffff0000, v123
	v_mul_f32_e32 v122, v122, v123
	v_cvt_pk_bf16_f32 v122, v122, s0
	ds_write_b16 v146, v122 offset:384
	ds_read_b64 v[122:123], v169 offset:1536
	s_waitcnt lgkmcnt(0)
	v_lshlrev_b32_e32 v136, 16, v122
	v_and_b32_e32 v137, 0xffff0000, v122
	v_lshlrev_b32_e32 v122, 16, v123
	v_and_b32_e32 v123, 0xffff0000, v123
	v_pk_mul_f32 v[148:149], v[122:123], v[122:123]
	v_pk_mul_f32 v[142:143], v[136:137], v[136:137]
	s_nop 0
	v_mov_b32_dpp v148, v148 quad_perm:[1,0,3,2] row_mask:0xf bank_mask:0xf bound_ctrl:1
	v_mov_b32_dpp v142, v142 quad_perm:[1,0,3,2] row_mask:0xf bank_mask:0xf bound_ctrl:1
	v_mov_b32_dpp v143, v143 quad_perm:[1,0,3,2] row_mask:0xf bank_mask:0xf bound_ctrl:1
	v_mov_b32_dpp v149, v149 quad_perm:[1,0,3,2] row_mask:0xf bank_mask:0xf bound_ctrl:1
	v_pk_fma_f32 v[142:143], v[136:137], v[136:137], v[142:143]
	v_pk_fma_f32 v[148:149], v[122:123], v[122:123], v[148:149]
	s_nop 0
	v_mov_b32_dpp v146, v142 quad_perm:[2,3,0,1] row_mask:0xf bank_mask:0xf bound_ctrl:1
	v_mov_b32_dpp v147, v143 quad_perm:[2,3,0,1] row_mask:0xf bank_mask:0xf bound_ctrl:1
	v_mov_b32_dpp v150, v148 quad_perm:[2,3,0,1] row_mask:0xf bank_mask:0xf bound_ctrl:1
	v_mov_b32_dpp v151, v149 quad_perm:[2,3,0,1] row_mask:0xf bank_mask:0xf bound_ctrl:1
	v_pk_add_f32 v[142:143], v[142:143], v[146:147]
	v_pk_add_f32 v[148:149], v[148:149], v[150:151]
	s_nop 0
	v_mov_b32_dpp v146, v142 row_half_mirror row_mask:0xf bank_mask:0xf bound_ctrl:1
	v_mov_b32_dpp v147, v143 row_half_mirror row_mask:0xf bank_mask:0xf bound_ctrl:1
	v_mov_b32_dpp v150, v148 row_half_mirror row_mask:0xf bank_mask:0xf bound_ctrl:1
	v_mov_b32_dpp v151, v149 row_half_mirror row_mask:0xf bank_mask:0xf bound_ctrl:1
	v_pk_add_f32 v[142:143], v[142:143], v[146:147]
	v_pk_add_f32 v[148:149], v[148:149], v[150:151]
	s_nop 0
	v_mov_b32_dpp v146, v142 row_mirror row_mask:0xf bank_mask:0xf bound_ctrl:1
	v_mov_b32_dpp v147, v143 row_mirror row_mask:0xf bank_mask:0xf bound_ctrl:1
	v_mov_b32_dpp v150, v148 row_mirror row_mask:0xf bank_mask:0xf bound_ctrl:1
	v_mov_b32_dpp v151, v149 row_mirror row_mask:0xf bank_mask:0xf bound_ctrl:1
	s_and_saveexec_b64 s[10:11], s[2:3]
	v_pk_add_f32 v[148:149], v[148:149], v[150:151]
	v_pk_add_f32 v[146:147], v[142:143], v[146:147]
	ds_write_b128 v160, v[146:149] offset:192
	s_or_b64 exec, exec, s[10:11]
	v_mul_f32_e32 v136, v119, v136
	v_lshlrev_b32_e32 v142, 16, v114
	v_mul_f32_e32 v136, v136, v142
	v_cvt_pk_bf16_f32 v136, v136, s0
	v_add_u32_e32 v142, v121, v159
	ds_write_b16 v142, v136
	v_mul_f32_e32 v136, v119, v137
	v_and_b32_e32 v114, 0xffff0000, v114
	v_mul_f32_e32 v114, v136, v114
	v_cvt_pk_bf16_f32 v114, v114, s0
	ds_write_b16 v142, v114 offset:128
	v_mul_f32_e32 v114, v119, v122
	v_lshlrev_b32_e32 v122, 16, v115
	v_mul_f32_e32 v114, v114, v122
	v_cvt_pk_bf16_f32 v114, v114, s0
	ds_write_b16 v142, v114 offset:256
	v_mul_f32_e32 v114, v119, v123
	v_and_b32_e32 v115, 0xffff0000, v115
	v_mul_f32_e32 v114, v114, v115
	v_cvt_pk_bf16_f32 v114, v114, s0
	ds_write_b16 v142, v114 offset:384
.LBB0_685:
	s_min_u32 s10, s12, 0xfb
	v_lshl_add_u64 v[114:115], v[134:135], 0, s[4:5]
	s_lshl_b32 s10, s10, 13
	v_add_co_u32_e32 v114, vcc, 0x232ec000, v114
	s_add_i32 s62, s10, 0x8000
	s_nop 0
	v_addc_co_u32_e32 v115, vcc, 0, v115, vcc
	s_lshl_b32 s10, s62, 1
	s_mov_b32 s11, s63
	global_load_dwordx2 v[142:143], v[114:115], off nt
	global_load_dwordx2 v[136:137], v[114:115], off offset:32 nt
	global_load_dwordx2 v[122:123], v[114:115], off offset:64 nt
	s_nop 0
	global_load_dwordx2 v[114:115], v[114:115], off offset:96 nt
	s_waitcnt lgkmcnt(0)
	s_barrier
	s_waitcnt vmcnt(22)
	ds_write_b128 v118, v[42:45]
	ds_write_b128 v118, v[46:49] offset:17408
	ds_write_b128 v120, v[50:53] offset:34816
	ds_write_b128 v118, v[54:57] offset:4352
	ds_write_b128 v118, v[66:69] offset:21760
	ds_write_b128 v120, v[70:73] offset:39424
	ds_write_b128 v118, v[82:85] offset:8704
	ds_write_b128 v118, v[86:89] offset:26112
	ds_write_b128 v120, v[90:93] offset:44032
	ds_write_b128 v118, v[94:97] offset:13056
	ds_write_b128 v118, v[98:101] offset:30464
	ds_write_b128 v120, v[102:105] offset:48640
	ds_write_b128 v120, v[106:109] offset:53248
	ds_write_b128 v120, v[110:113] offset:57856
	v_lshl_add_u64 v[90:91], v[124:125], 0, s[10:11]
	v_add_co_u32_e32 v54, vcc, s82, v90
	v_lshl_add_u64 v[98:99], v[126:127], 0, s[10:11]
	s_nop 0
	v_addc_co_u32_e32 v55, vcc, 0, v91, vcc
	v_add_co_u32_e32 v66, vcc, s82, v98
	v_lshl_add_u64 v[100:101], v[128:129], 0, s[10:11]
	s_nop 0
	v_addc_co_u32_e32 v67, vcc, 0, v99, vcc
	v_add_co_u32_e32 v70, vcc, s82, v100
	global_load_dwordx4 v[42:45], v[90:91], off nt
	global_load_dwordx4 v[46:49], v[98:99], off nt
	v_addc_co_u32_e32 v71, vcc, 0, v101, vcc
	v_add_co_u32_e32 v82, vcc, s83, v90
	v_lshl_add_u64 v[106:107], v[130:131], 0, s[62:63]
	s_nop 0
	v_addc_co_u32_e32 v83, vcc, 0, v91, vcc
	v_add_co_u32_e32 v86, vcc, s83, v98
	global_load_dwordx4 v[50:53], v[100:101], off nt
	s_nop 0
	global_load_dwordx4 v[54:57], v[54:55], off nt
	v_addc_co_u32_e32 v87, vcc, 0, v99, vcc
	v_add_co_u32_e32 v92, vcc, s83, v100
	global_load_dwordx4 v[66:69], v[66:67], off nt
	s_nop 0
	global_load_dwordx4 v[70:73], v[70:71], off nt
	v_addc_co_u32_e32 v93, vcc, 0, v101, vcc
	v_add_co_u32_e32 v94, vcc, s88, v90
	global_load_dwordx4 v[82:85], v[82:83], off nt
	s_nop 0
	global_load_dwordx4 v[86:89], v[86:87], off nt
	v_addc_co_u32_e32 v95, vcc, 0, v91, vcc
	v_add_co_u32_e32 v98, vcc, s88, v98
	global_load_dwordx4 v[90:93], v[92:93], off nt
	s_nop 0
	global_load_dwordx4 v[94:97], v[94:95], off nt
	v_addc_co_u32_e32 v99, vcc, 0, v99, vcc
	v_add_co_u32_e32 v102, vcc, s88, v100
	s_nop 1
	v_addc_co_u32_e32 v103, vcc, 0, v101, vcc
	v_add_co_u32_e32 v110, vcc, s82, v106
	global_load_dwordx4 v[98:101], v[98:99], off nt
	s_nop 0
	global_load_dwordx4 v[102:105], v[102:103], off nt
	v_addc_co_u32_e32 v111, vcc, 0, v107, vcc
	global_load_dwordx4 v[106:109], v[106:107], off nt
	s_nop 0
	global_load_dwordx4 v[110:113], v[110:111], off nt
	s_waitcnt vmcnt(32)
	ds_read_b64 v[146:147], v168
	s_waitcnt lgkmcnt(0)
	v_lshlrev_b32_e32 v148, 16, v146
	v_and_b32_e32 v149, 0xffff0000, v146
	v_lshlrev_b32_e32 v146, 16, v147
	v_and_b32_e32 v147, 0xffff0000, v147
	v_pk_mul_f32 v[154:155], v[146:147], v[146:147]
	v_pk_mul_f32 v[150:151], v[148:149], v[148:149]
	s_nop 0
	v_mov_b32_dpp v154, v154 quad_perm:[1,0,3,2] row_mask:0xf bank_mask:0xf bound_ctrl:1
	v_mov_b32_dpp v150, v150 quad_perm:[1,0,3,2] row_mask:0xf bank_mask:0xf bound_ctrl:1
	v_mov_b32_dpp v151, v151 quad_perm:[1,0,3,2] row_mask:0xf bank_mask:0xf bound_ctrl:1
	v_mov_b32_dpp v155, v155 quad_perm:[1,0,3,2] row_mask:0xf bank_mask:0xf bound_ctrl:1
	v_pk_fma_f32 v[150:151], v[148:149], v[148:149], v[150:151]
	v_pk_fma_f32 v[154:155], v[146:147], v[146:147], v[154:155]
	s_nop 0
	v_mov_b32_dpp v152, v150 quad_perm:[2,3,0,1] row_mask:0xf bank_mask:0xf bound_ctrl:1
	v_mov_b32_dpp v153, v151 quad_perm:[2,3,0,1] row_mask:0xf bank_mask:0xf bound_ctrl:1
	v_mov_b32_dpp v156, v154 quad_perm:[2,3,0,1] row_mask:0xf bank_mask:0xf bound_ctrl:1
	v_mov_b32_dpp v157, v155 quad_perm:[2,3,0,1] row_mask:0xf bank_mask:0xf bound_ctrl:1
	v_pk_add_f32 v[150:151], v[150:151], v[152:153]
	v_pk_add_f32 v[154:155], v[154:155], v[156:157]
	s_nop 0
	v_mov_b32_dpp v152, v150 row_half_mirror row_mask:0xf bank_mask:0xf bound_ctrl:1
	v_mov_b32_dpp v153, v151 row_half_mirror row_mask:0xf bank_mask:0xf bound_ctrl:1
	v_mov_b32_dpp v156, v154 row_half_mirror row_mask:0xf bank_mask:0xf bound_ctrl:1
	v_mov_b32_dpp v157, v155 row_half_mirror row_mask:0xf bank_mask:0xf bound_ctrl:1
	v_pk_add_f32 v[150:151], v[150:151], v[152:153]
	v_pk_add_f32 v[154:155], v[154:155], v[156:157]
	s_nop 0
	v_mov_b32_dpp v152, v150 row_mirror row_mask:0xf bank_mask:0xf bound_ctrl:1
	v_mov_b32_dpp v153, v151 row_mirror row_mask:0xf bank_mask:0xf bound_ctrl:1
	v_mov_b32_dpp v156, v154 row_mirror row_mask:0xf bank_mask:0xf bound_ctrl:1
	v_mov_b32_dpp v157, v155 row_mirror row_mask:0xf bank_mask:0xf bound_ctrl:1
	s_and_saveexec_b64 s[10:11], s[2:3]
	v_pk_add_f32 v[154:155], v[154:155], v[156:157]
	v_pk_add_f32 v[152:153], v[150:151], v[152:153]
	ds_write_b128 v167, v[152:155]
	s_or_b64 exec, exec, s[10:11]
	v_mul_f32_e32 v148, v119, v148
	v_lshlrev_b32_e32 v150, 16, v144
	v_mul_f32_e32 v148, v148, v150
	v_cvt_pk_bf16_f32 v148, v148, s0
	v_add_u32_e32 v150, v166, v163
	ds_write_b16 v150, v148
	v_mul_f32_e32 v148, v119, v149
	v_and_b32_e32 v144, 0xffff0000, v144
	v_mul_f32_e32 v144, v148, v144
	v_cvt_pk_bf16_f32 v144, v144, s0
	ds_write_b16 v150, v144 offset:128
	v_mul_f32_e32 v144, v119, v146
	v_lshlrev_b32_e32 v146, 16, v145
	v_mul_f32_e32 v144, v144, v146
	v_cvt_pk_bf16_f32 v144, v144, s0
	ds_write_b16 v150, v144 offset:256
	v_mul_f32_e32 v144, v119, v147
	v_and_b32_e32 v145, 0xffff0000, v145
	v_mul_f32_e32 v144, v144, v145
	v_cvt_pk_bf16_f32 v144, v144, s0
	ds_write_b16 v150, v144 offset:384
	ds_read_b64 v[144:145], v168 offset:512
	s_waitcnt lgkmcnt(0)
	v_lshlrev_b32_e32 v146, 16, v144
	v_and_b32_e32 v147, 0xffff0000, v144
	v_lshlrev_b32_e32 v144, 16, v145
	v_and_b32_e32 v145, 0xffff0000, v145
	v_pk_mul_f32 v[152:153], v[144:145], v[144:145]
	v_pk_mul_f32 v[148:149], v[146:147], v[146:147]
	s_nop 0
	v_mov_b32_dpp v152, v152 quad_perm:[1,0,3,2] row_mask:0xf bank_mask:0xf bound_ctrl:1
	v_mov_b32_dpp v148, v148 quad_perm:[1,0,3,2] row_mask:0xf bank_mask:0xf bound_ctrl:1
	v_mov_b32_dpp v149, v149 quad_perm:[1,0,3,2] row_mask:0xf bank_mask:0xf bound_ctrl:1
	v_mov_b32_dpp v153, v153 quad_perm:[1,0,3,2] row_mask:0xf bank_mask:0xf bound_ctrl:1
	v_pk_fma_f32 v[148:149], v[146:147], v[146:147], v[148:149]
	v_pk_fma_f32 v[152:153], v[144:145], v[144:145], v[152:153]
	s_nop 0
	v_mov_b32_dpp v150, v148 quad_perm:[2,3,0,1] row_mask:0xf bank_mask:0xf bound_ctrl:1
	v_mov_b32_dpp v151, v149 quad_perm:[2,3,0,1] row_mask:0xf bank_mask:0xf bound_ctrl:1
	v_mov_b32_dpp v154, v152 quad_perm:[2,3,0,1] row_mask:0xf bank_mask:0xf bound_ctrl:1
	v_mov_b32_dpp v155, v153 quad_perm:[2,3,0,1] row_mask:0xf bank_mask:0xf bound_ctrl:1
	v_pk_add_f32 v[148:149], v[148:149], v[150:151]
	v_pk_add_f32 v[152:153], v[152:153], v[154:155]
	s_nop 0
	v_mov_b32_dpp v150, v148 row_half_mirror row_mask:0xf bank_mask:0xf bound_ctrl:1
	v_mov_b32_dpp v151, v149 row_half_mirror row_mask:0xf bank_mask:0xf bound_ctrl:1
	v_mov_b32_dpp v154, v152 row_half_mirror row_mask:0xf bank_mask:0xf bound_ctrl:1
	v_mov_b32_dpp v155, v153 row_half_mirror row_mask:0xf bank_mask:0xf bound_ctrl:1
	v_pk_add_f32 v[148:149], v[148:149], v[150:151]
	v_pk_add_f32 v[152:153], v[152:153], v[154:155]
	s_nop 0
	v_mov_b32_dpp v150, v148 row_mirror row_mask:0xf bank_mask:0xf bound_ctrl:1
	v_mov_b32_dpp v151, v149 row_mirror row_mask:0xf bank_mask:0xf bound_ctrl:1
	v_mov_b32_dpp v154, v152 row_mirror row_mask:0xf bank_mask:0xf bound_ctrl:1
	v_mov_b32_dpp v155, v153 row_mirror row_mask:0xf bank_mask:0xf bound_ctrl:1
	s_and_saveexec_b64 s[10:11], s[2:3]
	v_pk_add_f32 v[152:153], v[152:153], v[154:155]
	v_pk_add_f32 v[150:151], v[148:149], v[150:151]
	ds_write_b128 v167, v[150:153] offset:64
	s_or_b64 exec, exec, s[10:11]
	v_mul_f32_e32 v146, v119, v146
	v_lshlrev_b32_e32 v148, 16, v140
	v_mul_f32_e32 v146, v146, v148
	v_cvt_pk_bf16_f32 v146, v146, s0
	v_add_u32_e32 v148, v166, v162
	ds_write_b16 v148, v146
	v_mul_f32_e32 v146, v119, v147
	v_and_b32_e32 v140, 0xffff0000, v140
	v_mul_f32_e32 v140, v146, v140
	v_cvt_pk_bf16_f32 v140, v140, s0
	ds_write_b16 v148, v140 offset:128
	v_mul_f32_e32 v140, v119, v144
	v_lshlrev_b32_e32 v144, 16, v141
	v_mul_f32_e32 v140, v140, v144
	v_cvt_pk_bf16_f32 v140, v140, s0
	ds_write_b16 v148, v140 offset:256
	v_mul_f32_e32 v140, v119, v145
	v_and_b32_e32 v141, 0xffff0000, v141
	v_mul_f32_e32 v140, v140, v141
	v_cvt_pk_bf16_f32 v140, v140, s0
	ds_write_b16 v148, v140 offset:384
	ds_read_b64 v[140:141], v168 offset:1024
	s_waitcnt lgkmcnt(0)
	v_lshlrev_b32_e32 v144, 16, v140
	v_and_b32_e32 v145, 0xffff0000, v140
	v_lshlrev_b32_e32 v140, 16, v141
	v_and_b32_e32 v141, 0xffff0000, v141
	v_pk_mul_f32 v[150:151], v[140:141], v[140:141]
	v_pk_mul_f32 v[146:147], v[144:145], v[144:145]
	s_nop 0
	v_mov_b32_dpp v150, v150 quad_perm:[1,0,3,2] row_mask:0xf bank_mask:0xf bound_ctrl:1
	v_mov_b32_dpp v146, v146 quad_perm:[1,0,3,2] row_mask:0xf bank_mask:0xf bound_ctrl:1
	v_mov_b32_dpp v147, v147 quad_perm:[1,0,3,2] row_mask:0xf bank_mask:0xf bound_ctrl:1
	v_mov_b32_dpp v151, v151 quad_perm:[1,0,3,2] row_mask:0xf bank_mask:0xf bound_ctrl:1
	v_pk_fma_f32 v[146:147], v[144:145], v[144:145], v[146:147]
	v_pk_fma_f32 v[150:151], v[140:141], v[140:141], v[150:151]
	s_nop 0
	v_mov_b32_dpp v148, v146 quad_perm:[2,3,0,1] row_mask:0xf bank_mask:0xf bound_ctrl:1
	v_mov_b32_dpp v149, v147 quad_perm:[2,3,0,1] row_mask:0xf bank_mask:0xf bound_ctrl:1
	v_mov_b32_dpp v152, v150 quad_perm:[2,3,0,1] row_mask:0xf bank_mask:0xf bound_ctrl:1
	v_mov_b32_dpp v153, v151 quad_perm:[2,3,0,1] row_mask:0xf bank_mask:0xf bound_ctrl:1
	v_pk_add_f32 v[146:147], v[146:147], v[148:149]
	v_pk_add_f32 v[150:151], v[150:151], v[152:153]
	s_nop 0
	v_mov_b32_dpp v148, v146 row_half_mirror row_mask:0xf bank_mask:0xf bound_ctrl:1
	v_mov_b32_dpp v149, v147 row_half_mirror row_mask:0xf bank_mask:0xf bound_ctrl:1
	v_mov_b32_dpp v152, v150 row_half_mirror row_mask:0xf bank_mask:0xf bound_ctrl:1
	v_mov_b32_dpp v153, v151 row_half_mirror row_mask:0xf bank_mask:0xf bound_ctrl:1
	v_pk_add_f32 v[146:147], v[146:147], v[148:149]
	v_pk_add_f32 v[150:151], v[150:151], v[152:153]
	s_nop 0
	v_mov_b32_dpp v148, v146 row_mirror row_mask:0xf bank_mask:0xf bound_ctrl:1
	v_mov_b32_dpp v149, v147 row_mirror row_mask:0xf bank_mask:0xf bound_ctrl:1
	v_mov_b32_dpp v152, v150 row_mirror row_mask:0xf bank_mask:0xf bound_ctrl:1
	v_mov_b32_dpp v153, v151 row_mirror row_mask:0xf bank_mask:0xf bound_ctrl:1
	s_and_saveexec_b64 s[10:11], s[2:3]
	v_pk_add_f32 v[150:151], v[150:151], v[152:153]
	v_pk_add_f32 v[148:149], v[146:147], v[148:149]
	ds_write_b128 v167, v[148:151] offset:128
	s_or_b64 exec, exec, s[10:11]
	v_mul_f32_e32 v144, v119, v144
	v_lshlrev_b32_e32 v146, 16, v138
	v_mul_f32_e32 v144, v144, v146
	v_cvt_pk_bf16_f32 v144, v144, s0
	v_add_u32_e32 v146, v166, v161
	ds_write_b16 v146, v144
	v_mul_f32_e32 v144, v119, v145
	v_and_b32_e32 v138, 0xffff0000, v138
	v_mul_f32_e32 v138, v144, v138
	v_cvt_pk_bf16_f32 v138, v138, s0
	ds_write_b16 v146, v138 offset:128
	v_mul_f32_e32 v138, v119, v140
	v_lshlrev_b32_e32 v140, 16, v139
	v_mul_f32_e32 v138, v138, v140
	v_cvt_pk_bf16_f32 v138, v138, s0
	ds_write_b16 v146, v138 offset:256
	v_mul_f32_e32 v138, v119, v141
	v_and_b32_e32 v139, 0xffff0000, v139
	v_mul_f32_e32 v138, v138, v139
	v_cvt_pk_bf16_f32 v138, v138, s0
	ds_write_b16 v146, v138 offset:384
	ds_read_b64 v[138:139], v168 offset:1536
	s_waitcnt lgkmcnt(0)
	v_lshlrev_b32_e32 v140, 16, v138
	v_and_b32_e32 v141, 0xffff0000, v138
	v_lshlrev_b32_e32 v138, 16, v139
	v_and_b32_e32 v139, 0xffff0000, v139
	v_pk_mul_f32 v[148:149], v[138:139], v[138:139]
	v_pk_mul_f32 v[144:145], v[140:141], v[140:141]
	s_nop 0
	v_mov_b32_dpp v148, v148 quad_perm:[1,0,3,2] row_mask:0xf bank_mask:0xf bound_ctrl:1
	v_mov_b32_dpp v144, v144 quad_perm:[1,0,3,2] row_mask:0xf bank_mask:0xf bound_ctrl:1
	v_mov_b32_dpp v145, v145 quad_perm:[1,0,3,2] row_mask:0xf bank_mask:0xf bound_ctrl:1
	v_mov_b32_dpp v149, v149 quad_perm:[1,0,3,2] row_mask:0xf bank_mask:0xf bound_ctrl:1
	v_pk_fma_f32 v[144:145], v[140:141], v[140:141], v[144:145]
	v_pk_fma_f32 v[148:149], v[138:139], v[138:139], v[148:149]
	s_nop 0
	v_mov_b32_dpp v146, v144 quad_perm:[2,3,0,1] row_mask:0xf bank_mask:0xf bound_ctrl:1
	v_mov_b32_dpp v147, v145 quad_perm:[2,3,0,1] row_mask:0xf bank_mask:0xf bound_ctrl:1
	v_mov_b32_dpp v150, v148 quad_perm:[2,3,0,1] row_mask:0xf bank_mask:0xf bound_ctrl:1
	v_mov_b32_dpp v151, v149 quad_perm:[2,3,0,1] row_mask:0xf bank_mask:0xf bound_ctrl:1
	v_pk_add_f32 v[144:145], v[144:145], v[146:147]
	v_pk_add_f32 v[148:149], v[148:149], v[150:151]
	s_nop 0
	v_mov_b32_dpp v146, v144 row_half_mirror row_mask:0xf bank_mask:0xf bound_ctrl:1
	v_mov_b32_dpp v147, v145 row_half_mirror row_mask:0xf bank_mask:0xf bound_ctrl:1
	v_mov_b32_dpp v150, v148 row_half_mirror row_mask:0xf bank_mask:0xf bound_ctrl:1
	v_mov_b32_dpp v151, v149 row_half_mirror row_mask:0xf bank_mask:0xf bound_ctrl:1
	v_pk_add_f32 v[144:145], v[144:145], v[146:147]
	v_pk_add_f32 v[148:149], v[148:149], v[150:151]
	s_nop 0
	v_mov_b32_dpp v146, v144 row_mirror row_mask:0xf bank_mask:0xf bound_ctrl:1
	v_mov_b32_dpp v147, v145 row_mirror row_mask:0xf bank_mask:0xf bound_ctrl:1
	v_mov_b32_dpp v150, v148 row_mirror row_mask:0xf bank_mask:0xf bound_ctrl:1
	v_mov_b32_dpp v151, v149 row_mirror row_mask:0xf bank_mask:0xf bound_ctrl:1
	s_and_saveexec_b64 s[10:11], s[2:3]
	s_cbranch_execz .LBB0_674
	v_pk_add_f32 v[148:149], v[148:149], v[150:151]
	v_pk_add_f32 v[146:147], v[144:145], v[146:147]
	ds_write_b128 v167, v[146:149] offset:192
	s_branch .LBB0_674
